# sample-row GEMM loads issued ahead with counted waits; FFN-up epilogue row-scale loads hoisted; loop code placement pads; barrier acquire earlier
# speedup vs baseline: 1.0028x; 1.0028x over previous
; #define LAS __attribute__((address_space(3)))
; DI void ti_load(f32x4 (&v)[8], float (&g)[8], const TItem& ti) {
; #pragma unroll
;     for (int i = 0; i < 8; ++i) v[i] = *(const f32x4*)(ti.src + (size_t)(8 * i) * ti.N);
; #pragma unroll
;     for (int i = 0; i < 8; ++i) g[i] = ti.gp[8 * i];
; }
; template <int NS>
; DI void convert_flat(const CStack (&st)[NS], LAS float* scr, int gw, int NGW, int lane) {
;     const int total = cstack_total(st);
;     int it = gw;
;     if (it >= total) return;
;     TItem cur, nxt; f32x4 va[8], vb[8]; float ga[8], gb[8];
;     ti_decode(cur, it, st, lane); ti_load(va, ga, cur);
.LBB0_39:
	s_mov_b32 s39, 0
	s_lshl_b32 s38, s44, 5
	v_lshl_add_u64 v[2:3], v[78:79], 0, s[38:39]
	v_lshl_add_u64 v[10:11], v[2:3], 0, s[38:39]
	global_load_dwordx4 v[2:5], v[2:3], off
	s_nop 0
	global_load_dwordx4 v[6:9], v[10:11], off
	v_lshl_add_u64 v[10:11], v[10:11], 0, s[38:39]
	v_lshl_add_u64 v[18:19], v[10:11], 0, s[38:39]
	global_load_dwordx4 v[10:13], v[10:11], off
	s_nop 0
	global_load_dwordx4 v[14:17], v[18:19], off
	v_lshl_add_u64 v[18:19], v[18:19], 0, s[38:39]
	v_lshl_add_u64 v[26:27], v[18:19], 0, s[38:39]
	global_load_dwordx4 v[18:21], v[18:19], off
	s_nop 0
	global_load_dwordx4 v[22:25], v[26:27], off
	v_lshl_add_u64 v[26:27], v[26:27], 0, s[38:39]
	global_load_dword v96, v[82:83], off
	global_load_dword v97, v[82:83], off offset:32
	global_load_dword v98, v[82:83], off offset:64
	global_load_dword v99, v[82:83], off offset:96
	global_load_dword v100, v[82:83], off offset:128
	global_load_dword v101, v[82:83], off offset:160
	global_load_dword v102, v[82:83], off offset:192
	global_load_dword v103, v[82:83], off offset:224
	global_load_dwordx4 v[30:33], v[26:27], off
	s_nop 0
	global_load_dwordx4 v[26:29], v[78:79], off
	s_mulk_i32 s43, 0x2400
	s_add_i32 s38, s43, 0
	v_mov_b32_e32 v69, 0
	v_mov_b32_e32 v73, v69
	s_cmp_lg_u64 s[24:25], 0
	v_lshl_add_u64 v[76:77], s[40:41], 0, v[72:73]
	s_cselect_b64 s[40:41], -1, 0
	s_cmp_lg_u64 s[0:1], 0
	v_lshl_add_u32 v34, v34, 2, s38
	v_mul_u32_u24_e32 v36, 0x90, v90
	v_lshl_add_u32 v37, v1, 2, s38
	v_mul_u32_u24_e32 v35, 0x90, v35
	v_lshl_add_u64 v[74:75], s[0:1], 0, v[72:73]
	s_cselect_b64 s[0:1], -1, 0
	v_cndmask_b32_e64 v91, 0, 1, s[0:1]
	v_mov_b32_e32 v94, s48
	s_movk_i32 s60, 0xa00
	v_add_u32_e32 v92, v34, v36
	v_add_u32_e32 v93, v37, v35
	s_mov_b32 s61, s20
	s_branch .LBB0_43

; #define LAS __attribute__((address_space(3)))
; DI unsigned pk2(float a, float b) { f32x2 v = {a, b}; hbf16x2 r = __builtin_convertvector(v, hbf16x2); return __builtin_bit_cast(unsigned, r); }
; DI void ti_load(f32x4 (&v)[8], float (&g)[8], const TItem& ti) {
; #pragma unroll
;     for (int i = 0; i < 8; ++i) v[i] = *(const f32x4*)(ti.src + (size_t)(8 * i) * ti.N);
; #pragma unroll
;     for (int i = 0; i < 8; ++i) g[i] = ti.gp[8 * i];
; }
; DI void ti_finish(const f32x4 (&v)[8], const float (&g)[8], const TItem& ti, LAS float* scr, int lane) {
;     const int q8 = lane & 7, kr = lane >> 3;
; #pragma unroll
;     for (int i = 0; i < 8; ++i) *(LAS f32x4*)(scr + (8 * i + kr) * 36 + 4 * q8) = v[i] * (ti.hasg ? g[i] : 1.0f);
;     asm volatile("s_waitcnt lgkmcnt(0)" ::: "memory");
;     const int n = lane & 31, kc = lane >> 5;
; #pragma unroll
;     for (int p2 = 0; p2 < 4; ++p2) { const int c = 2 * p2 + kc; const LAS float* s = scr + (8 * c) * 36 + n;
;         u32x4 o; o.x = pk2(s[0], s[36]); o.y = pk2(s[72], s[108]); o.z = pk2(s[144], s[180]); o.w = pk2(s[216], s[252]);
;         *(u32x4*)(ti.dst + 16 * p2) = o; }
;     asm volatile("s_waitcnt lgkmcnt(0)" ::: "memory");
; }
.LBB0_41:
	s_lshl_b64 s[48:49], s[48:49], 5
	global_load_dwordx4 v[26:29], v[2:3], off
	v_lshl_add_u64 v[2:3], v[2:3], 0, s[48:49]
	v_lshl_add_u64 v[10:11], v[2:3], 0, s[48:49]
	global_load_dwordx4 v[2:5], v[2:3], off
	s_nop 0
	global_load_dwordx4 v[6:9], v[10:11], off
	v_lshl_add_u64 v[10:11], v[10:11], 0, s[48:49]
	v_lshl_add_u64 v[18:19], v[10:11], 0, s[48:49]
	global_load_dwordx4 v[10:13], v[10:11], off
	s_nop 0
	global_load_dwordx4 v[14:17], v[18:19], off
	v_lshl_add_u64 v[18:19], v[18:19], 0, s[48:49]
	v_lshl_add_u64 v[30:31], v[18:19], 0, s[48:49]
	global_load_dwordx4 v[18:21], v[18:19], off
	s_nop 0
	global_load_dwordx4 v[22:25], v[30:31], off
	v_lshl_add_u64 v[30:31], v[30:31], 0, s[48:49]
	global_load_dwordx4 v[30:33], v[30:31], off
	s_nop 0
	global_load_dword v96, v[82:83], off
	global_load_dword v97, v[82:83], off offset:32
	global_load_dword v98, v[82:83], off offset:64
	global_load_dword v99, v[82:83], off offset:96
	global_load_dword v100, v[82:83], off offset:128
	global_load_dword v101, v[82:83], off offset:160
	global_load_dword v102, v[82:83], off offset:192
	global_load_dword v103, v[82:83], off offset:224
	v_cmp_eq_u32_e32 vcc, 0, v95
	s_and_b64 s[48:49], s[46:47], exec
	s_cselect_b32 s61, s45, s61
	s_waitcnt vmcnt(31)
	v_cndmask_b32_e64 v118, v117, 1.0, vcc
	s_waitcnt vmcnt(20)
	v_pk_mul_f32 v[64:65], v[64:65], v[118:119] op_sel_hi:[1,0]
	v_pk_mul_f32 v[62:63], v[62:63], v[118:119] op_sel_hi:[1,0]
	ds_write_b128 v92, v[62:65]
	v_cndmask_b32_e64 v62, v116, 1.0, vcc
	v_pk_mul_f32 v[48:49], v[48:49], v[62:63] op_sel_hi:[1,0]
	v_pk_mul_f32 v[46:47], v[46:47], v[62:63] op_sel_hi:[1,0]
	ds_write_b128 v92, v[46:49] offset:1152
	v_cndmask_b32_e64 v46, v115, 1.0, vcc
	v_pk_mul_f32 v[44:45], v[44:45], v[46:47] op_sel_hi:[1,0]
	v_pk_mul_f32 v[42:43], v[42:43], v[46:47] op_sel_hi:[1,0]
	ds_write_b128 v92, v[42:45] offset:2304
	v_cndmask_b32_e64 v42, v114, 1.0, vcc
	v_pk_mul_f32 v[40:41], v[40:41], v[42:43] op_sel_hi:[1,0]
	v_pk_mul_f32 v[38:39], v[38:39], v[42:43] op_sel_hi:[1,0]
	ds_write_b128 v92, v[38:41] offset:3456
	v_cndmask_b32_e64 v38, v112, 1.0, vcc
	v_pk_mul_f32 v[36:37], v[36:37], v[38:39] op_sel_hi:[1,0]
	v_pk_mul_f32 v[34:35], v[34:35], v[38:39] op_sel_hi:[1,0]
	ds_write_b128 v92, v[34:37] offset:4608
	v_cndmask_b32_e64 v34, v106, 1.0, vcc
	v_pk_mul_f32 v[36:37], v[60:61], v[34:35] op_sel_hi:[1,0]
	v_pk_mul_f32 v[34:35], v[58:59], v[34:35] op_sel_hi:[1,0]
	ds_write_b128 v92, v[34:37] offset:5760
	v_cndmask_b32_e64 v34, v105, 1.0, vcc
	v_pk_mul_f32 v[36:37], v[56:57], v[34:35] op_sel_hi:[1,0]
	v_pk_mul_f32 v[34:35], v[54:55], v[34:35] op_sel_hi:[1,0]
	ds_write_b128 v92, v[34:37] offset:6912
	v_cndmask_b32_e64 v34, v104, 1.0, vcc
	v_pk_mul_f32 v[36:37], v[52:53], v[34:35] op_sel_hi:[1,0]
	v_pk_mul_f32 v[34:35], v[50:51], v[34:35] op_sel_hi:[1,0]
	ds_write_b128 v92, v[34:37] offset:8064
	s_waitcnt lgkmcnt(0)
	ds_read2_b32 v[34:35], v93 offset1:36
	ds_read2_b32 v[36:37], v93 offset0:72 offset1:108
	ds_read2_b32 v[38:39], v93 offset0:144 offset1:180
	ds_read2_b32 v[40:41], v93 offset0:216 offset1:252
	s_waitcnt lgkmcnt(3)
	v_cvt_pk_bf16_f32 v34, v34, v35
	s_waitcnt lgkmcnt(2)
	v_cvt_pk_bf16_f32 v35, v36, v37
	s_waitcnt lgkmcnt(1)
	v_cvt_pk_bf16_f32 v36, v38, v39
	s_waitcnt lgkmcnt(0)
	v_cvt_pk_bf16_f32 v37, v40, v41
	ds_read2_b32 v[38:39], v107 offset0:64 offset1:100
	ds_read2_b32 v[40:41], v107 offset0:136 offset1:172
	ds_read2_b32 v[42:43], v107 offset0:208 offset1:244
	ds_read2_b32 v[44:45], v109 offset0:24 offset1:60
	global_store_dwordx4 v[88:89], v[34:37], off
	s_waitcnt lgkmcnt(3)
	s_nop 0
	v_cvt_pk_bf16_f32 v34, v38, v39
	s_waitcnt lgkmcnt(2)
	v_cvt_pk_bf16_f32 v35, v40, v41
	s_waitcnt lgkmcnt(1)
	v_cvt_pk_bf16_f32 v36, v42, v43
	s_waitcnt lgkmcnt(0)
	v_cvt_pk_bf16_f32 v37, v44, v45
	ds_read2_b32 v[38:39], v108 offset0:128 offset1:164
	ds_read2_b32 v[40:41], v108 offset0:200 offset1:236
	ds_read2_b32 v[42:43], v110 offset0:16 offset1:52
	ds_read2_b32 v[44:45], v110 offset0:88 offset1:124
	global_store_dwordx4 v[88:89], v[34:37], off offset:32
	s_waitcnt lgkmcnt(3)
	s_nop 0
	v_cvt_pk_bf16_f32 v34, v38, v39
	s_waitcnt lgkmcnt(2)
	v_cvt_pk_bf16_f32 v35, v40, v41
	s_waitcnt lgkmcnt(1)
	v_cvt_pk_bf16_f32 v36, v42, v43
	s_waitcnt lgkmcnt(0)
	v_cvt_pk_bf16_f32 v37, v44, v45
	ds_read2_b32 v[38:39], v113 offset0:192 offset1:228
	ds_read2_b32 v[40:41], v111 offset0:8 offset1:44
	ds_read2_b32 v[42:43], v111 offset0:80 offset1:116
	ds_read2_b32 v[44:45], v111 offset0:152 offset1:188
	global_store_dwordx4 v[88:89], v[34:37], off offset:64
	s_waitcnt lgkmcnt(3)
	s_nop 0
	v_cvt_pk_bf16_f32 v34, v38, v39
	s_waitcnt lgkmcnt(2)
	v_cvt_pk_bf16_f32 v35, v40, v41
	s_waitcnt lgkmcnt(1)
	v_cvt_pk_bf16_f32 v36, v42, v43
	s_waitcnt lgkmcnt(0)
	v_cvt_pk_bf16_f32 v37, v44, v45
	global_store_dwordx4 v[88:89], v[34:37], off offset:96
	s_waitcnt lgkmcnt(0)

; #define LAS __attribute__((address_space(3)))
; DI unsigned pk2(float a, float b) { f32x2 v = {a, b}; hbf16x2 r = __builtin_convertvector(v, hbf16x2); return __builtin_bit_cast(unsigned, r); }
; template <int NS>
; DI void ti_decode(TItem& ti, int it, const CStack (&st)[NS], int lane) {
;     int base = 0;
; #pragma unroll
;     for (int j = 0; j < NS; ++j) {
;         const int nblk = st[j].N / 32, per = (st[j].K / 64) * nblk, tot = st[j].L * per;
;         if (it >= base && (it < base + tot || j == NS - 1)) {
;             const int K = st[j].K, N = st[j].N, r0 = it - base, l = r0 / per, rem = r0 - l * per, kb = rem / nblk, nb = rem - kb * nblk, k0 = 64 * kb;
;             ti.src = st[j].W + (size_t)l * K * N + (size_t)(k0 + (lane >> 3)) * N + (st[j].perm ? even_src32(nb) : 32 * nb) + 4 * (lane & 7);
;             ti.dst = st[j].WT + (size_t)l * K * N + (size_t)(32 * nb + (lane & 31)) * K + k0 + 8 * (lane >> 5);
;             ti.hasg = st[j].gk != nullptr; ti.gp = ti.hasg ? st[j].gk + (size_t)l * st[j].gstride + k0 + (lane >> 3) : ti.src;
;             ti.N = N;
;         }
;         base += tot;
;     }
; }
; DI void ti_load(f32x4 (&v)[8], float (&g)[8], const TItem& ti) {
; #pragma unroll
;     for (int i = 0; i < 8; ++i) v[i] = *(const f32x4*)(ti.src + (size_t)(8 * i) * ti.N);
; #pragma unroll
;     for (int i = 0; i < 8; ++i) g[i] = ti.gp[8 * i];
; }
; DI void ti_finish(const f32x4 (&v)[8], const float (&g)[8], const TItem& ti, LAS float* scr, int lane) {
;     const int q8 = lane & 7, kr = lane >> 3;
; #pragma unroll
;     for (int i = 0; i < 8; ++i) *(LAS f32x4*)(scr + (8 * i + kr) * 36 + 4 * q8) = v[i] * (ti.hasg ? g[i] : 1.0f);
;     asm volatile("s_waitcnt lgkmcnt(0)" ::: "memory");
;     const int n = lane & 31, kc = lane >> 5;
; #pragma unroll
;     for (int p2 = 0; p2 < 4; ++p2) { const int c = 2 * p2 + kc; const LAS float* s = scr + (8 * c) * 36 + n;
;         u32x4 o; o.x = pk2(s[0], s[36]); o.y = pk2(s[72], s[108]); o.z = pk2(s[144], s[180]); o.w = pk2(s[216], s[252]);
;         *(u32x4*)(ti.dst + 16 * p2) = o; }
;     asm volatile("s_waitcnt lgkmcnt(0)" ::: "memory");
; }
.LBB0_72:
	s_lshl_b64 s[48:49], s[48:49], 5
	v_lshl_add_u64 v[34:35], v[84:85], 0, s[48:49]
	v_lshl_add_u64 v[36:37], v[34:35], 0, s[48:49]
	global_load_dwordx4 v[46:49], v[34:35], off
	global_load_dwordx4 v[42:45], v[36:37], off
	v_lshl_add_u64 v[34:35], v[36:37], 0, s[48:49]
	s_waitcnt vmcnt(7)
	v_lshl_add_u64 v[50:51], v[34:35], 0, s[48:49]
	global_load_dwordx4 v[38:41], v[34:35], off
	s_nop 0
	global_load_dwordx4 v[34:37], v[50:51], off
	global_load_dword v117, v[86:87], off
	global_load_dword v116, v[86:87], off offset:32
	global_load_dword v115, v[86:87], off offset:64
	global_load_dword v114, v[86:87], off offset:96
	global_load_dword v112, v[86:87], off offset:128
	global_load_dword v106, v[86:87], off offset:160
	global_load_dword v105, v[86:87], off offset:192
	global_load_dword v104, v[86:87], off offset:224
	v_lshl_add_u64 v[50:51], v[50:51], 0, s[48:49]
	v_lshl_add_u64 v[52:53], v[50:51], 0, s[48:49]
	v_cmp_eq_u32_e32 vcc, 0, v94
	s_waitcnt vmcnt(16)
	v_lshl_add_u64 v[62:63], v[52:53], 0, s[48:49]
	v_add_u32_e32 v107, 0x800, v93
	s_waitcnt vmcnt(21)
	v_cndmask_b32_e64 v54, v96, 1.0, vcc
	s_waitcnt vmcnt(12)
	v_pk_mul_f32 v[110:111], v[28:29], v[54:55] op_sel_hi:[1,0]
	v_pk_mul_f32 v[108:109], v[26:27], v[54:55] op_sel_hi:[1,0]
	global_load_dwordx4 v[58:61], v[50:51], off
	global_load_dwordx4 v[54:57], v[52:53], off
	s_nop 0
	global_load_dwordx4 v[50:53], v[62:63], off
	s_nop 0
	global_load_dwordx4 v[62:65], v[84:85], off
	ds_write_b128 v92, v[108:111]
	v_cndmask_b32_e64 v108, v97, 1.0, vcc
	v_pk_mul_f32 v[110:111], v[4:5], v[108:109] op_sel_hi:[1,0]
	v_pk_mul_f32 v[108:109], v[2:3], v[108:109] op_sel_hi:[1,0]
	ds_write_b128 v92, v[108:111] offset:1152
	v_cndmask_b32_e64 v108, v98, 1.0, vcc
	v_pk_mul_f32 v[110:111], v[8:9], v[108:109] op_sel_hi:[1,0]
	v_pk_mul_f32 v[108:109], v[6:7], v[108:109] op_sel_hi:[1,0]
	ds_write_b128 v92, v[108:111] offset:2304
	v_cndmask_b32_e64 v108, v99, 1.0, vcc
	v_pk_mul_f32 v[110:111], v[12:13], v[108:109] op_sel_hi:[1,0]
	v_pk_mul_f32 v[108:109], v[10:11], v[108:109] op_sel_hi:[1,0]
	ds_write_b128 v92, v[108:111] offset:3456
	v_cndmask_b32_e64 v108, v100, 1.0, vcc
	v_pk_mul_f32 v[110:111], v[16:17], v[108:109] op_sel_hi:[1,0]
	v_pk_mul_f32 v[108:109], v[14:15], v[108:109] op_sel_hi:[1,0]
	ds_write_b128 v92, v[108:111] offset:4608
	v_cndmask_b32_e64 v108, v101, 1.0, vcc
	v_pk_mul_f32 v[110:111], v[20:21], v[108:109] op_sel_hi:[1,0]
	v_pk_mul_f32 v[108:109], v[18:19], v[108:109] op_sel_hi:[1,0]
	ds_write_b128 v92, v[108:111] offset:5760
	v_cndmask_b32_e64 v108, v102, 1.0, vcc
	v_pk_mul_f32 v[110:111], v[24:25], v[108:109] op_sel_hi:[1,0]
	v_pk_mul_f32 v[108:109], v[22:23], v[108:109] op_sel_hi:[1,0]
	ds_write_b128 v92, v[108:111] offset:6912
	v_cndmask_b32_e64 v108, v103, 1.0, vcc
	v_pk_mul_f32 v[110:111], v[32:33], v[108:109] op_sel_hi:[1,0]
	v_pk_mul_f32 v[108:109], v[30:31], v[108:109] op_sel_hi:[1,0]
	ds_write_b128 v92, v[108:111] offset:8064
	s_waitcnt lgkmcnt(0)
	ds_read2_b32 v[108:109], v93 offset1:36
	ds_read2_b32 v[110:111], v93 offset0:72 offset1:108
	ds_read2_b32 v[120:121], v93 offset0:144 offset1:180
	ds_read2_b32 v[122:123], v93 offset0:216 offset1:252
	v_add_u32_e32 v113, 0x1800, v93
	s_waitcnt lgkmcnt(3)
	v_cvt_pk_bf16_f32 v118, v108, v109
	v_add_u32_e32 v109, 0xc00, v93
	s_waitcnt lgkmcnt(2)
	v_cvt_pk_bf16_f32 v119, v110, v111
	s_waitcnt lgkmcnt(1)
	v_cvt_pk_bf16_f32 v120, v120, v121
	s_waitcnt lgkmcnt(0)
	v_cvt_pk_bf16_f32 v121, v122, v123
	ds_read2_b32 v[110:111], v107 offset0:64 offset1:100
	ds_read2_b32 v[122:123], v107 offset0:136 offset1:172
	ds_read2_b32 v[124:125], v107 offset0:208 offset1:244
	ds_read2_b32 v[126:127], v109 offset0:24 offset1:60
	global_store_dwordx4 v[80:81], v[118:121], off
	v_add_u32_e32 v108, 0x1000, v93
	s_andn2_b64 vcc, exec, s[46:47]
	s_waitcnt lgkmcnt(3)
	v_cvt_pk_bf16_f32 v118, v110, v111
	v_add_u32_e32 v110, 0x1400, v93
	s_waitcnt lgkmcnt(2)
	v_cvt_pk_bf16_f32 v119, v122, v123
	s_waitcnt lgkmcnt(1)
	v_cvt_pk_bf16_f32 v120, v124, v125
	s_waitcnt lgkmcnt(0)
	v_cvt_pk_bf16_f32 v121, v126, v127
	ds_read2_b32 v[122:123], v108 offset0:128 offset1:164
	ds_read2_b32 v[124:125], v108 offset0:200 offset1:236
	ds_read2_b32 v[126:127], v110 offset0:16 offset1:52
	ds_read2_b32 v[128:129], v110 offset0:88 offset1:124
	global_store_dwordx4 v[80:81], v[118:121], off offset:32
	v_add_u32_e32 v111, 0x1c00, v93
	s_mov_b64 s[46:47], 0
	s_waitcnt lgkmcnt(3)
	v_cvt_pk_bf16_f32 v118, v122, v123
	s_waitcnt lgkmcnt(2)
	v_cvt_pk_bf16_f32 v119, v124, v125
	s_waitcnt lgkmcnt(1)
	v_cvt_pk_bf16_f32 v120, v126, v127
	s_waitcnt lgkmcnt(0)
	v_cvt_pk_bf16_f32 v121, v128, v129
	ds_read2_b32 v[122:123], v113 offset0:192 offset1:228
	ds_read2_b32 v[124:125], v111 offset0:8 offset1:44
	ds_read2_b32 v[126:127], v111 offset0:80 offset1:116
	ds_read2_b32 v[128:129], v111 offset0:152 offset1:188
	global_store_dwordx4 v[80:81], v[118:121], off offset:64
	s_waitcnt lgkmcnt(3)
	s_nop 0
	v_cvt_pk_bf16_f32 v118, v122, v123
	s_waitcnt lgkmcnt(2)
	v_cvt_pk_bf16_f32 v119, v124, v125
	s_waitcnt lgkmcnt(1)
	v_cvt_pk_bf16_f32 v120, v126, v127
	s_waitcnt lgkmcnt(0)
	v_cvt_pk_bf16_f32 v121, v128, v129
	global_store_dwordx4 v[80:81], v[118:121], off offset:96
	s_waitcnt lgkmcnt(0)
	s_cbranch_vccnz .LBB0_42
	s_add_i32 s45, s43, s18
	s_cmp_lt_i32 s45, 0x10400
	s_cselect_b64 s[46:47], -1, 0
	s_and_b64 s[48:49], s[46:47], exec
	s_cselect_b32 s62, s45, s43
	s_cmpk_gt_u32 s62, 0x23ff
	s_cbranch_scc1 .LBB0_92
	s_cmpk_gt_u32 s62, 0x11ff
	s_cselect_b64 s[42:43], -1, 0
	s_and_b64 s[48:49], s[42:43], exec
	s_cselect_b32 s38, 0xffffee00, 0
	s_add_i32 s38, s38, s62
	s_mul_i32 s48, s38, 0xe39
	s_lshr_b32 s49, s48, 31
	s_ashr_i32 s48, s48, 19
	s_add_i32 s49, s48, s49
	s_mul_i32 s48, s49, 0xffffff70
	s_add_i32 s48, s48, s38
	s_lshl_b32 s38, s48, 5
	s_ashr_i32 s64, s48, 3
	s_bfe_u32 s63, s38, 0x10007
	s_and_b32 s65, s62, 3
	s_cmp_gt_i32 s64, 3
	s_mov_b64 s[50:51], -1
	s_cbranch_scc0 .LBB0_80
	s_cmp_lg_u32 s64, 4
	s_cbranch_scc0 .LBB0_77
	s_and_b32 s48, s38, 0xe0
	s_cmpk_lt_u32 s48, 0x80
	s_cselect_b32 s48, s60, 0xe00
	s_lshl_b32 s50, s64, 7
	s_and_b32 s51, s38, 0x60
	s_or_b32 s50, s50, s51
	s_add_i32 s48, s50, s48
	s_addk_i32 s48, 0xfb00
	s_cmp_lt_u32 s64, 10
	s_cselect_b32 s48, s38, s48
	s_mov_b64 s[50:51], 0

; DI unsigned pk2(float a, float b) { f32x2 v = {a, b}; hbf16x2 r = __builtin_convertvector(v, hbf16x2); return __builtin_bit_cast(unsigned, r); }
; __global__ void __launch_bounds__(512, 2) fwd_kernel(Args a) {
;     ...
;         for (int r = gw; r < MT; r += NGW) {
;             const f32x4* xi = (const f32x4*)((r < MP) ? xp + (size_t)r * DM : xs + (size_t)(r - MP) * DM) + lane;
;             f32x4 xv[8]; float s = 0.f;
; #pragma unroll
;             for (int j = 0; j < 8; ++j) { xv[j] = xi[64 * j]; s += (xv[j][0] * xv[j][0] + xv[j][1] * xv[j][1]) + (xv[j][2] * xv[j][2] + xv[j][3] * xv[j][3]); }
;             const float rstd = 1.0f / sqrtf(wave_sum(s) * (1.0f / DM) + EPSN);
;             if (lane == 0) RS[r] = rstd;
;             u32x2* hp = (u32x2*)(H + (size_t)r * DM) + lane;
; #pragma unroll
;             for (int j = 0; j < 8; ++j) { u32x2 w; w.x = pk2(xv[j][0], xv[j][1]); w.y = pk2(xv[j][2], xv[j][3]); hp[64 * j] = w; }
;         }
.LBB0_104:
	s_add_i32 s4, s20, 0xffffe000
	s_cmpk_lt_i32 s20, 0x2000
	s_cselect_b32 s5, s21, 0
	s_cselect_b32 s4, s20, s4
	s_waitcnt lgkmcnt(0)
	s_cselect_b32 s14, s9, s11
	s_cselect_b32 s15, s8, s10
	s_lshl_b64 s[4:5], s[4:5], 13
	s_add_u32 s4, s15, s4
	s_addc_u32 s5, s14, s5
	global_load_dwordx4 v[6:9], v34, s[4:5]
	global_load_dwordx4 v[2:5], v34, s[4:5] offset:1024
	global_load_dwordx4 v[10:13], v34, s[4:5] offset:2048
	global_load_dwordx4 v[14:17], v34, s[4:5] offset:3072
	s_waitcnt vmcnt(18)
	v_lshl_add_u64 v[18:19], s[4:5], 0, v[34:35]
	v_add_co_u32_e32 v46, vcc, s24, v18
	s_waitcnt vmcnt(2)
	v_mul_f32_e32 v48, v3, v3
	v_addc_co_u32_e32 v47, vcc, 0, v19, vcc
	global_load_dwordx4 v[18:21], v[46:47], off
	global_load_dwordx4 v[22:25], v[46:47], off offset:1024
	global_load_dwordx4 v[26:29], v[46:47], off offset:2048
	global_load_dwordx4 v[30:33], v[46:47], off offset:3072
	v_mul_f32_e32 v46, v7, v7
	v_mul_f32_e32 v47, v9, v9
	v_mul_f32_e32 v49, v5, v5
	s_waitcnt vmcnt(5)
	v_mul_f32_e32 v50, v11, v11
	v_mul_f32_e32 v51, v13, v13
	v_fmac_f32_e32 v46, v6, v6
	v_fmac_f32_e32 v47, v8, v8
	v_fmac_f32_e32 v48, v2, v2
	v_fmac_f32_e32 v49, v4, v4
	s_waitcnt vmcnt(4)
	v_mul_f32_e32 v52, v15, v15
	v_mul_f32_e32 v53, v17, v17
	v_fmac_f32_e32 v50, v10, v10
	v_fmac_f32_e32 v51, v12, v12
	v_add_f32_e32 v46, v46, v47
	v_add_f32_e32 v47, v48, v49
	v_fmac_f32_e32 v52, v14, v14
	v_fmac_f32_e32 v53, v16, v16
	v_add_f32_e32 v48, v50, v51
	v_add_f32_e32 v46, v46, v47
	v_add_f32_e32 v49, v52, v53
	v_add_f32_e32 v46, v46, v48
	v_add_f32_e32 v46, v46, v49
	s_waitcnt vmcnt(3)
	v_mul_f32_e32 v50, v19, v19
	v_mul_f32_e32 v51, v21, v21
	s_waitcnt vmcnt(2)
	v_mul_f32_e32 v52, v23, v23
	v_mul_f32_e32 v53, v25, v25
	v_fmac_f32_e32 v50, v18, v18
	v_fmac_f32_e32 v51, v20, v20
	s_waitcnt vmcnt(1)
	v_mul_f32_e32 v54, v27, v27
	v_mul_f32_e32 v55, v29, v29
	v_fmac_f32_e32 v52, v22, v22
	v_fmac_f32_e32 v53, v24, v24
	v_add_f32_e32 v47, v50, v51
	s_waitcnt vmcnt(0)
	v_mul_f32_e32 v56, v31, v31
	v_mul_f32_e32 v57, v33, v33
	v_fmac_f32_e32 v54, v26, v26
	v_fmac_f32_e32 v55, v28, v28
	v_add_f32_e32 v48, v52, v53
	v_add_f32_e32 v46, v46, v47
	v_fmac_f32_e32 v56, v30, v30
	v_fmac_f32_e32 v57, v32, v32
	v_add_f32_e32 v50, v54, v55
	v_add_f32_e32 v46, v46, v48
	v_add_f32_e32 v46, v46, v50
	v_add_f32_e32 v47, v56, v57
	v_add_f32_e32 v46, v46, v47
	ds_bpermute_b32 v47, v38, v46
	s_waitcnt lgkmcnt(0)
	v_add_f32_e32 v46, v46, v47
	ds_bpermute_b32 v47, v39, v46
	s_waitcnt lgkmcnt(0)
	v_add_f32_e32 v46, v46, v47
	ds_bpermute_b32 v47, v40, v46
	s_waitcnt lgkmcnt(0)
	v_add_f32_e32 v46, v46, v47
	ds_bpermute_b32 v47, v41, v46
	s_waitcnt lgkmcnt(0)
	v_add_f32_e32 v46, v46, v47
	ds_bpermute_b32 v47, v42, v46
	s_waitcnt lgkmcnt(0)
	v_add_f32_e32 v46, v46, v47
	ds_bpermute_b32 v47, v43, v46
	s_and_saveexec_b64 s[14:15], s[0:1]
	s_cbranch_execz .LBB0_103
	s_waitcnt lgkmcnt(0)
	v_add_f32_e32 v46, v46, v47
	v_fmamk_f32 v46, v46, 0x3a000000, v44
	v_mul_f32_e32 v47, 0x4f800000, v46
	v_cmp_gt_f32_e32 vcc, s25, v46
	s_nop 1
	v_cndmask_b32_e32 v46, v46, v47, vcc
	v_sqrt_f32_e32 v47, v46
	s_nop 0
	v_add_u32_e32 v48, -1, v47
	v_fma_f32 v50, -v48, v47, v46
	v_add_u32_e32 v49, 1, v47
	v_cmp_ge_f32_e64 s[4:5], 0, v50
	s_nop 1
	v_cndmask_b32_e64 v48, v47, v48, s[4:5]
	v_fma_f32 v47, -v49, v47, v46
	v_cmp_lt_f32_e64 s[4:5], 0, v47
	s_nop 1
	v_cndmask_b32_e64 v47, v48, v49, s[4:5]
	v_mul_f32_e32 v48, 0x37800000, v47
	v_cndmask_b32_e32 v47, v47, v48, vcc
	v_cmp_class_f32_e32 vcc, v46, v45
	s_nop 1
	v_cndmask_b32_e32 v46, v47, v46, vcc
	v_div_scale_f32 v47, s[4:5], v46, v46, 1.0
	v_rcp_f32_e32 v48, v47
	s_add_u32 s4, s16, s22
	s_addc_u32 s5, s17, s23
	v_fma_f32 v49, -v47, v48, 1.0
	v_fmac_f32_e32 v48, v49, v48
	v_div_scale_f32 v49, vcc, 1.0, v46, 1.0
	v_mul_f32_e32 v50, v49, v48
	v_fma_f32 v51, -v47, v50, v49
	v_fmac_f32_e32 v50, v51, v48
	v_fma_f32 v47, -v47, v50, v49
	v_div_fmas_f32 v47, v47, v48, v50
	v_div_fixup_f32 v46, v47, v46, 1.0
	global_store_dword v35, v46, s[4:5]
	s_branch .LBB0_103

; #define LAS __attribute__((address_space(3)))
; #define MFMA16(a, b, c) __builtin_amdgcn_mfma_f32_16x16x32_bf16((a), (b), (c), 0, 0, 0)
; DI unsigned short f2bf1(float a) { return (unsigned short)(pk2(a, 0.f) & 0xffffu); }
;     ...
;     const int ntask = (N / (16 * NC)) * KSPLIT, kr = K / KSPLIT, kw = kr / 8;
;     LAS float* red = (LAS float*)lds;
;     for (int t = G - 1 - cu; t < ntask; t += G) {
;         const int cgi = t / KSPLIT, kh = t - cgi * KSPLIT, n0 = cgi * 16 * NC, kbeg = kh * kr + wid * kw + 8 * fq;
;         const bf16* wp = WT + (size_t)(n0 + fr) * K + kbeg;
;         const bf16* ap0 = As + (size_t)fr * K + kbeg; const bf16* ap1 = ap0 + (size_t)16 * K;
;         f32x4 acc[NC][2];
; #pragma unroll
;         for (int c = 0; c < NC; ++c) { acc[c][0] = (f32x4){0.f, 0.f, 0.f, 0.f}; acc[c][1] = (f32x4){0.f, 0.f, 0.f, 0.f}; }
; #pragma unroll 4
;         for (int k = 0; k < kw; k += 32) {
;             const bf16x8 a0 = *(const bf16x8*)(ap0 + k), a1 = *(const bf16x8*)(ap1 + k);
; #pragma unroll
;             for (int c = 0; c < NC; ++c) { const bf16x8 w = *(const bf16x8*)(wp + (size_t)c * 16 * K + k); acc[c][0] = MFMA16(w, a0, acc[c][0]); acc[c][1] = MFMA16(w, a1, acc[c][1]); }
;         }
; #pragma unroll
;         for (int c = 0; c < NC; ++c) { *(LAS f32x4*)(red + (wid * NC + c) * 512 + fr * 16 + 4 * fq) = acc[c][0]; *(LAS f32x4*)(red + (wid * NC + c) * 512 + (16 + fr) * 16 + 4 * fq) = acc[c][1]; }
;         __syncthreads();
; #pragma unroll
;         for (int c = 0; c < NC; ++c) {
;             float s = 0.f;
; #pragma unroll
;             for (int w = 0; w < 8; ++w) s += red[(w * NC + c) * 512 + tid];
;             const int row = tid >> 4, n = tid & 15, nn = n0 + 16 * c;
;             if (rsv) s *= rsv[row];
;             if (MODE == 0) { const int col = evenperm ? even_src32(nn >> 5) + (nn & 16) + n : nn + n; outf[(size_t)(kh * 32 + row) * ldo + col] = s; }
;             else if (MODE == 1) { const float r = fmaxf(s, 0.f); outb[(size_t)row * ldo + nn + n] = f2bf1(r * r); }
;             else outb[(size_t)row * ldo + nn + n] = f2bf1(s);
;         }
.LBB0_273:
	v_lshl_add_u64 v[30:31], v[20:21], 0, v[12:13]
	v_lshl_add_u64 v[42:43], v[18:19], 0, v[12:13]
	v_add_co_u32_e32 v38, vcc, 0x18400000, v30
	s_nop 1
	v_addc_co_u32_e32 v39, vcc, 0, v31, vcc
	v_add_co_u32_e32 v40, vcc, 0x18410000, v30
	s_nop 1
	v_addc_co_u32_e32 v41, vcc, 0, v31, vcc
	global_load_dwordx4 v[44:47], v[42:43], off offset:-128
	global_load_dwordx4 v[48:51], v[38:39], off
	global_load_dwordx4 v[52:55], v[40:41], off
	global_load_dwordx4 v[56:59], v[42:43], off offset:-64
	global_load_dwordx4 v[60:63], v[38:39], off offset:64
	global_load_dwordx4 v[64:67], v[40:41], off offset:64
	global_load_dwordx4 v[68:71], v[42:43], off
	global_load_dwordx4 v[72:75], v[38:39], off offset:128
	global_load_dwordx4 v[76:79], v[40:41], off offset:128
	global_load_dwordx4 v[80:83], v[42:43], off offset:64
	global_load_dwordx4 v[84:87], v[38:39], off offset:192
	global_load_dwordx4 v[88:91], v[40:41], off offset:192
	global_load_dwordx4 v[92:95], v[42:43], off offset:128
	global_load_dwordx4 v[96:99], v[38:39], off offset:256
	global_load_dwordx4 v[100:103], v[40:41], off offset:256
	global_load_dwordx4 v[104:107], v[42:43], off offset:192
	global_load_dwordx4 v[108:111], v[38:39], off offset:320
	global_load_dwordx4 v[112:115], v[40:41], off offset:320
	global_load_dwordx4 v[116:119], v[42:43], off offset:256
	global_load_dwordx4 v[120:123], v[38:39], off offset:384
	global_load_dwordx4 v[124:127], v[40:41], off offset:384
	global_load_dwordx4 v[128:131], v[42:43], off offset:320
	global_load_dwordx4 v[132:135], v[38:39], off offset:448
	global_load_dwordx4 v[136:139], v[40:41], off offset:448
	s_waitcnt vmcnt(21)
	v_mfma_f32_16x16x32_bf16 v[0:3], v[44:47], v[48:51], v[0:3]
	v_mfma_f32_16x16x32_bf16 v[4:7], v[44:47], v[52:55], v[4:7]
	s_waitcnt vmcnt(18)
	v_mfma_f32_16x16x32_bf16 v[0:3], v[56:59], v[60:63], v[0:3]
	v_mfma_f32_16x16x32_bf16 v[4:7], v[56:59], v[64:67], v[4:7]
	s_waitcnt vmcnt(15)
	v_mfma_f32_16x16x32_bf16 v[0:3], v[68:71], v[72:75], v[0:3]
	v_mfma_f32_16x16x32_bf16 v[4:7], v[68:71], v[76:79], v[4:7]
	s_waitcnt vmcnt(12)
	v_mfma_f32_16x16x32_bf16 v[0:3], v[80:83], v[84:87], v[0:3]
	v_mfma_f32_16x16x32_bf16 v[4:7], v[80:83], v[88:91], v[4:7]
	s_waitcnt vmcnt(9)
	v_mfma_f32_16x16x32_bf16 v[0:3], v[92:95], v[96:99], v[0:3]
	v_mfma_f32_16x16x32_bf16 v[4:7], v[92:95], v[100:103], v[4:7]
	s_waitcnt vmcnt(6)
	v_mfma_f32_16x16x32_bf16 v[0:3], v[104:107], v[108:111], v[0:3]
	v_mfma_f32_16x16x32_bf16 v[4:7], v[104:107], v[112:115], v[4:7]
	s_waitcnt vmcnt(3)
	v_mfma_f32_16x16x32_bf16 v[0:3], v[116:119], v[120:123], v[0:3]
	v_mfma_f32_16x16x32_bf16 v[4:7], v[116:119], v[124:127], v[4:7]
	s_waitcnt vmcnt(0)
	v_mfma_f32_16x16x32_bf16 v[0:3], v[128:131], v[132:135], v[0:3]
	v_mfma_f32_16x16x32_bf16 v[4:7], v[128:131], v[136:139], v[4:7]
	s_nop 5
	ds_write_b128 v23, v[0:3]
	ds_write_b128 v23, v[4:7] offset:1024
	s_waitcnt lgkmcnt(0)
	s_barrier
	global_load_dword v3, v[8:9], off
	ds_read2st64_b32 v[0:1], v24 offset1:8
	v_lshl_or_b32 v18, s2, 4, v22
	v_ashrrev_i32_e32 v19, 31, v18
	s_add_i32 s2, s2, s90
	v_add_u32_e32 v16, s61, v16
	s_waitcnt lgkmcnt(0)
	v_add_f32_e32 v0, 0, v0
	v_add_f32_e32 v2, v0, v1
	ds_read2st64_b32 v[0:1], v24 offset0:16 offset1:24
	s_cmpk_gt_i32 s2, 0xff
	s_waitcnt lgkmcnt(0)
	v_add_f32_e32 v0, v2, v0
	v_add_f32_e32 v2, v0, v1
	ds_read2st64_b32 v[0:1], v24 offset0:32 offset1:40
	s_waitcnt lgkmcnt(0)
	v_add_f32_e32 v0, v2, v0
	v_add_f32_e32 v2, v0, v1
	ds_read2st64_b32 v[0:1], v24 offset0:48 offset1:56
	s_waitcnt lgkmcnt(0)
	v_add_f32_e32 v0, v2, v0
	v_add_f32_e32 v2, v0, v1
	v_lshl_add_u64 v[0:1], v[18:19], 2, v[10:11]
	s_waitcnt vmcnt(0)
	v_mul_f32_e32 v2, v2, v3
	global_store_dword v[0:1], v2, off
	s_barrier
	s_cbranch_scc0 .LBB0_272

; template <class Epi, class Sched, bool ALIGN_EPI = false, bool SP2 = false>
; __device__ __forceinline__ void gemm_phase(PG8_LAS unsigned char* lds, const Gemm g, const Sched& S, const Epi& E) {
;     ...
;         const bool has_next = S.next(ui + 1, nxt);
;         const char* nA = has_next ? (const char*)g.A + (size_t)nxt.pm * tstep : cA; const char* nB = has_next ? (const char*)g.Bt + (size_t)nxt.pn * tstep : cB;
;         for (int t = 0; t < nt; t += 2) {
;     ...
; #pragma unroll
;         for (int a = 0; a < 2; ++a)
; #pragma unroll
;             for (int b = 0; b < 2; ++b)
; #pragma unroll
;                 for (int m = 0; m < 4; ++m)
; #pragma unroll
;                     for (int n = 0; n < 2; ++n) acc[a][b][m][n] = (f32x4){0.f, 0.f, 0.f, 0.f};
;         cur = nxt; cA = nA; cB = nB; ++ui;
.LBB0_1057:
	s_ashr_i32 s21, s20, 31
	s_lshl_b64 s[22:23], s[20:21], 20
	s_add_u32 s22, s12, s22
	s_addc_u32 s23, s13, s23
	s_and_b64 s[24:25], s[0:1], exec
	s_cselect_b32 s21, s23, s27
	s_cselect_b32 s47, s22, s26
	s_ashr_i32 s19, s18, 31
	s_lshl_b64 s[24:25], s[18:19], 20
	s_add_u32 s24, s33, s24
	s_addc_u32 s25, s34, s25
	s_and_b64 s[30:31], s[0:1], exec
	s_cselect_b32 s19, s25, s29
	s_cselect_b32 s48, s24, s28
	s_add_u32 s26, s26, 0x80080
	s_addc_u32 s27, s27, 0
	s_add_u32 s49, s28, 0x100
	v_mov_b32_e32 v0, 0
	s_addc_u32 s50, s29, 0
	s_mov_b32 s51, -2
	v_mov_b32_e32 v1, v0
	v_mov_b32_e32 v2, v0
	v_mov_b32_e32 v3, v0
	v_mov_b32_e32 v4, v0
	v_mov_b32_e32 v5, v0
	v_mov_b32_e32 v6, v0
	v_mov_b32_e32 v7, v0
	v_mov_b32_e32 v16, v0
	v_mov_b32_e32 v17, v0
	v_mov_b32_e32 v18, v0
	v_mov_b32_e32 v19, v0
	v_mov_b32_e32 v20, v0
	v_mov_b32_e32 v21, v0
	v_mov_b32_e32 v22, v0
	v_mov_b32_e32 v23, v0
	v_mov_b32_e32 v32, v0
	v_mov_b32_e32 v33, v0
	v_mov_b32_e32 v34, v0
	v_mov_b32_e32 v35, v0
	v_mov_b32_e32 v36, v0
	v_mov_b32_e32 v37, v0
	v_mov_b32_e32 v38, v0
	v_mov_b32_e32 v39, v0
	v_mov_b32_e32 v48, v0
	v_mov_b32_e32 v49, v0
	v_mov_b32_e32 v50, v0
	v_mov_b32_e32 v51, v0
	v_mov_b32_e32 v52, v0
	v_mov_b32_e32 v53, v0
	v_mov_b32_e32 v54, v0
	v_mov_b32_e32 v55, v0
	v_mov_b32_e32 v8, v0
	v_mov_b32_e32 v9, v0
	v_mov_b32_e32 v10, v0
	v_mov_b32_e32 v11, v0
	v_mov_b32_e32 v12, v0
	v_mov_b32_e32 v13, v0
	v_mov_b32_e32 v14, v0
	v_mov_b32_e32 v15, v0
	v_mov_b32_e32 v24, v0
	v_mov_b32_e32 v25, v0
	v_mov_b32_e32 v26, v0
	v_mov_b32_e32 v27, v0
	v_mov_b32_e32 v28, v0
	v_mov_b32_e32 v29, v0
	v_mov_b32_e32 v30, v0
	v_mov_b32_e32 v31, v0
	v_mov_b32_e32 v40, v0
	v_mov_b32_e32 v41, v0
	v_mov_b32_e32 v42, v0
	v_mov_b32_e32 v43, v0
	v_mov_b32_e32 v44, v0
	v_mov_b32_e32 v45, v0
	v_mov_b32_e32 v46, v0
	v_mov_b32_e32 v47, v0
	v_mov_b32_e32 v56, v0
	v_mov_b32_e32 v57, v0
	v_mov_b32_e32 v58, v0
	v_mov_b32_e32 v59, v0
	v_mov_b32_e32 v60, v0
	v_mov_b32_e32 v61, v0
	v_mov_b32_e32 v62, v0
	v_mov_b32_e32 v63, v0
	v_mov_b32_e32 v64, v0
	v_mov_b32_e32 v65, v0
	v_mov_b32_e32 v66, v0
	v_mov_b32_e32 v67, v0
	v_mov_b32_e32 v68, v0
	v_mov_b32_e32 v69, v0
	v_mov_b32_e32 v70, v0
	v_mov_b32_e32 v71, v0
	v_mov_b32_e32 v80, v0
	v_mov_b32_e32 v81, v0
	v_mov_b32_e32 v82, v0
	v_mov_b32_e32 v83, v0
	v_mov_b32_e32 v84, v0
	v_mov_b32_e32 v85, v0
	v_mov_b32_e32 v86, v0
	v_mov_b32_e32 v87, v0
	v_mov_b32_e32 v96, v0
	v_mov_b32_e32 v97, v0
	v_mov_b32_e32 v98, v0
	v_mov_b32_e32 v99, v0
	v_mov_b32_e32 v100, v0
	v_mov_b32_e32 v101, v0
	v_mov_b32_e32 v102, v0
	v_mov_b32_e32 v103, v0
	v_mov_b32_e32 v112, v0
	v_mov_b32_e32 v113, v0
	v_mov_b32_e32 v114, v0
	v_mov_b32_e32 v115, v0
	v_mov_b32_e32 v116, v0
	v_mov_b32_e32 v117, v0
	v_mov_b32_e32 v118, v0
	v_mov_b32_e32 v119, v0
	v_mov_b32_e32 v72, v0
	v_mov_b32_e32 v73, v0
	v_mov_b32_e32 v74, v0
	v_mov_b32_e32 v75, v0
	v_mov_b32_e32 v76, v0
	v_mov_b32_e32 v77, v0
	v_mov_b32_e32 v78, v0
	v_mov_b32_e32 v79, v0
	v_mov_b32_e32 v88, v0
	v_mov_b32_e32 v89, v0
	v_mov_b32_e32 v90, v0
	v_mov_b32_e32 v91, v0
	v_mov_b32_e32 v92, v0
	v_mov_b32_e32 v93, v0
	v_mov_b32_e32 v94, v0
	v_mov_b32_e32 v95, v0
	v_mov_b32_e32 v104, v0
	v_mov_b32_e32 v105, v0
	v_mov_b32_e32 v106, v0
	v_mov_b32_e32 v107, v0
	v_mov_b32_e32 v108, v0
	v_mov_b32_e32 v109, v0
	v_mov_b32_e32 v110, v0
	v_mov_b32_e32 v111, v0
	v_mov_b32_e32 v120, v0
	v_mov_b32_e32 v121, v0
	v_mov_b32_e32 v122, v0
	v_mov_b32_e32 v123, v0
	v_mov_b32_e32 v124, v0
	v_mov_b32_e32 v125, v0
	v_mov_b32_e32 v126, v0
	v_mov_b32_e32 v127, v0
	s_nop 0
	s_nop 0

; DI u32x4 pk8(f32x4 a, f32x4 b) { u32x4 w; w.x = pk2(a[0], a[1]); w.y = pk2(a[2], a[3]); w.z = pk2(b[0], b[1]); w.w = pk2(b[2], b[3]); return w; }
;     DI void operator()(const f32x4 (&acc)[2][2][4][2], const Unit& u, int wr, int wc, int fr, int fq) const {
;     ...
;         const int row0 = u.pm * BM + wr * 64 + fr, col0 = u.pn * BM + wc * 32 + 8 * fq;
; #pragma unroll
;         for (int ai = 0; ai < 2; ++ai)
; #pragma unroll
;             for (int m = 0; m < 4; ++m) { bf16* rowp = O + (size_t)(row0 + ai * HALF + m * 16) * ldc + col0; const float rs = RS[row0 + ai * HALF + m * 16];
; #pragma unroll
;                 for (int bj = 0; bj < 2; ++bj) { f32x4 v0 = acc[ai][bj][m][0], v1 = acc[ai][bj][m][1];
; #pragma unroll
;                     for (int e = 0; e < 4; ++e) { const float a = fmaxf(v0[e] * rs, 0.f), b = fmaxf(v1[e] * rs, 0.f); v0[e] = a * a; v1[e] = b * b; }
;                     *(u32x4*)(rowp + bj * HALF) = pk8(v0, v1); } }
.LBB0_1061:
	v_mov_b32_e32 v138, v142
	v_mov_b32_e32 v146, v143
	s_lshl_b32 s19, s46, 8
	s_add_i32 s19, s19, s40
	v_add_u32_e32 v138, s19, v138
	v_ashrrev_i32_e32 v139, 31, v138
	v_lshl_add_u64 v[140:141], v[138:139], 2, s[14:15]
	global_load_dword v148, v[140:141], off
	global_load_dword v200, v[140:141], off offset:64
	global_load_dword v201, v[140:141], off offset:128
	global_load_dword v202, v[140:141], off offset:192
	global_load_dword v203, v[140:141], off offset:512
	global_load_dword v204, v[140:141], off offset:576
	global_load_dword v205, v[140:141], off offset:640
	global_load_dword v206, v[140:141], off offset:704
	s_lshl_b32 s19, s45, 8
	s_or_b32 s19, s19, s41
	v_lshl_add_u32 v146, v146, 3, s19
	v_lshlrev_b64 v[138:139], 14, v[138:139]
	v_ashrrev_i32_e32 v147, 31, v146
	v_lshl_add_u64 v[138:139], s[4:5], 0, v[138:139]
	v_lshl_add_u64 v[138:139], v[146:147], 1, v[138:139]
	s_mov_b32 s19, 0x40000
	s_mov_b64 s[26:27], 0x40000
	s_waitcnt vmcnt(0)
	v_mul_f32_e32 v124, v124, v148
	v_mul_f32_e32 v120, v120, v148
	v_mul_f32_e32 v125, v125, v148
	v_mul_f32_e32 v121, v121, v148
	v_mul_f32_e32 v126, v126, v148
	v_mul_f32_e32 v122, v122, v148
	v_mul_f32_e32 v127, v127, v148
	v_mul_f32_e32 v123, v123, v148
	v_mul_f32_e32 v146, v116, v148
	v_mul_f32_e32 v147, v112, v148
	v_mul_f32_e32 v149, v117, v148
	v_mul_f32_e32 v150, v113, v148
	v_mul_f32_e32 v151, v118, v148
	v_mul_f32_e32 v164, v114, v148
	v_mul_f32_e32 v165, v119, v148
	v_mul_f32_e32 v148, v115, v148
	v_max_f32_e32 v112, 0, v124
	v_max_f32_e32 v114, 0, v120
	v_max_f32_e32 v113, 0, v125
	v_max_f32_e32 v115, 0, v121
	v_max_f32_e32 v116, 0, v126
	v_max_f32_e32 v118, 0, v122
	v_max_f32_e32 v117, 0, v127
	v_max_f32_e32 v119, 0, v123
	v_max_f32_e32 v120, 0, v146
	v_max_f32_e32 v122, 0, v147
	v_max_f32_e32 v121, 0, v149
	v_max_f32_e32 v123, 0, v150
	v_max_f32_e32 v124, 0, v151
	v_max_f32_e32 v126, 0, v164
	v_max_f32_e32 v125, 0, v165
	v_max_f32_e32 v127, 0, v148
	v_pk_mul_f32 v[112:113], v[112:113], v[112:113]
	v_pk_mul_f32 v[114:115], v[114:115], v[114:115]
	v_pk_mul_f32 v[116:117], v[116:117], v[116:117]
	v_pk_mul_f32 v[118:119], v[118:119], v[118:119]
	v_pk_mul_f32 v[120:121], v[120:121], v[120:121]
	v_pk_mul_f32 v[122:123], v[122:123], v[122:123]
	v_pk_mul_f32 v[124:125], v[124:125], v[124:125]
	v_pk_mul_f32 v[126:127], v[126:127], v[126:127]
	v_cvt_pk_bf16_f32 v112, v112, v113
	v_cvt_pk_bf16_f32 v113, v116, v117
	v_cvt_pk_bf16_f32 v114, v114, v115
	v_cvt_pk_bf16_f32 v115, v118, v119
	v_cvt_pk_bf16_f32 v116, v120, v121
	v_cvt_pk_bf16_f32 v117, v124, v125
	v_cvt_pk_bf16_f32 v118, v122, v123
	v_cvt_pk_bf16_f32 v119, v126, v127
	global_store_dwordx4 v[138:139], v[112:115], off
	global_store_dwordx4 v[138:139], v[116:119], off offset:256
	s_nop 0
	v_add_co_u32_e32 v114, vcc, s19, v138
	v_lshl_add_u64 v[112:113], v[138:139], 0, s[26:27]
	s_nop 0
	v_addc_co_u32_e32 v115, vcc, 0, v139, vcc
	s_mov_b32 s19, 0x80000
	s_mov_b64 s[26:27], 0x80000
	v_mov_b32_e32 v116, v200
	v_mul_f32_e32 v108, v108, v116
	v_mul_f32_e32 v104, v104, v116
	v_mul_f32_e32 v109, v109, v116
	v_mul_f32_e32 v105, v105, v116
	v_mul_f32_e32 v110, v110, v116
	v_mul_f32_e32 v106, v106, v116
	v_mul_f32_e32 v111, v111, v116
	v_mul_f32_e32 v107, v107, v116
	v_mul_f32_e32 v117, v100, v116
	v_mul_f32_e32 v118, v96, v116
	v_mul_f32_e32 v119, v101, v116
	v_mul_f32_e32 v120, v97, v116
	v_mul_f32_e32 v121, v102, v116
	v_mul_f32_e32 v122, v98, v116
	v_mul_f32_e32 v123, v103, v116
	v_mul_f32_e32 v116, v99, v116
	v_max_f32_e32 v96, 0, v108
	v_max_f32_e32 v98, 0, v104
	v_max_f32_e32 v97, 0, v109
	v_max_f32_e32 v99, 0, v105
	v_max_f32_e32 v100, 0, v110
	v_max_f32_e32 v102, 0, v106
	v_max_f32_e32 v101, 0, v111
	v_max_f32_e32 v103, 0, v107
	v_max_f32_e32 v104, 0, v117
	v_max_f32_e32 v106, 0, v118
	v_max_f32_e32 v105, 0, v119
	v_max_f32_e32 v107, 0, v120
	v_max_f32_e32 v108, 0, v121
	v_max_f32_e32 v110, 0, v122
	v_max_f32_e32 v109, 0, v123
	v_max_f32_e32 v111, 0, v116
	v_pk_mul_f32 v[96:97], v[96:97], v[96:97]
	v_pk_mul_f32 v[98:99], v[98:99], v[98:99]
	v_pk_mul_f32 v[100:101], v[100:101], v[100:101]
	v_pk_mul_f32 v[102:103], v[102:103], v[102:103]
	v_pk_mul_f32 v[104:105], v[104:105], v[104:105]
	v_pk_mul_f32 v[106:107], v[106:107], v[106:107]
	v_pk_mul_f32 v[108:109], v[108:109], v[108:109]
	v_pk_mul_f32 v[110:111], v[110:111], v[110:111]
	v_cvt_pk_bf16_f32 v96, v96, v97
	v_cvt_pk_bf16_f32 v97, v100, v101
	v_cvt_pk_bf16_f32 v98, v98, v99
	v_cvt_pk_bf16_f32 v99, v102, v103
	v_cvt_pk_bf16_f32 v100, v104, v105
	v_cvt_pk_bf16_f32 v101, v108, v109
	v_cvt_pk_bf16_f32 v102, v106, v107
	v_cvt_pk_bf16_f32 v103, v110, v111
	global_store_dwordx4 v[114:115], v[96:99], off
	global_store_dwordx4 v[112:113], v[100:103], off offset:256
	s_nop 0
	v_add_co_u32_e32 v98, vcc, s19, v138
	v_lshl_add_u64 v[96:97], v[138:139], 0, s[26:27]
	s_nop 0
	v_addc_co_u32_e32 v99, vcc, 0, v139, vcc
	s_mov_b32 s19, 0xc0000
	s_mov_b64 s[26:27], 0xc0000
	v_mov_b32_e32 v100, v201
	v_mul_f32_e32 v92, v92, v100
	v_mul_f32_e32 v88, v88, v100
	v_mul_f32_e32 v93, v93, v100
	v_mul_f32_e32 v89, v89, v100
	v_mul_f32_e32 v94, v94, v100
	v_mul_f32_e32 v90, v90, v100
	v_mul_f32_e32 v95, v95, v100
	v_mul_f32_e32 v91, v91, v100
	v_mul_f32_e32 v101, v84, v100
	v_mul_f32_e32 v102, v80, v100
	v_mul_f32_e32 v103, v85, v100
	v_mul_f32_e32 v104, v81, v100
	v_mul_f32_e32 v105, v86, v100
	v_mul_f32_e32 v106, v82, v100
	v_mul_f32_e32 v107, v87, v100
	v_mul_f32_e32 v100, v83, v100
	v_max_f32_e32 v80, 0, v92
	v_max_f32_e32 v82, 0, v88
	v_max_f32_e32 v81, 0, v93
	v_max_f32_e32 v83, 0, v89
	v_max_f32_e32 v84, 0, v94
	v_max_f32_e32 v86, 0, v90
	v_max_f32_e32 v85, 0, v95
	v_max_f32_e32 v87, 0, v91
; DI u32x4 pk8(f32x4 a, f32x4 b) { u32x4 w; w.x = pk2(a[0], a[1]); w.y = pk2(a[2], a[3]); w.z = pk2(b[0], b[1]); w.w = pk2(b[2], b[3]); return w; }
;     DI void operator()(const f32x4 (&acc)[2][2][4][2], const Unit& u, int wr, int wc, int fr, int fq) const {
;     ...
;         const int row0 = u.pm * BM + wr * 64 + fr, col0 = u.pn * BM + wc * 32 + 8 * fq;
; #pragma unroll
;         for (int ai = 0; ai < 2; ++ai)
; #pragma unroll
;             for (int m = 0; m < 4; ++m) { bf16* rowp = O + (size_t)(row0 + ai * HALF + m * 16) * ldc + col0; const float rs = RS[row0 + ai * HALF + m * 16];
; #pragma unroll
;                 for (int bj = 0; bj < 2; ++bj) { f32x4 v0 = acc[ai][bj][m][0], v1 = acc[ai][bj][m][1];
; #pragma unroll
;                     for (int e = 0; e < 4; ++e) { const float a = fmaxf(v0[e] * rs, 0.f), b = fmaxf(v1[e] * rs, 0.f); v0[e] = a * a; v1[e] = b * b; }
;                     *(u32x4*)(rowp + bj * HALF) = pk8(v0, v1); } }
	v_max_f32_e32 v88, 0, v101
	v_max_f32_e32 v90, 0, v102
	v_max_f32_e32 v89, 0, v103
	v_max_f32_e32 v91, 0, v104
	v_max_f32_e32 v92, 0, v105
	v_max_f32_e32 v94, 0, v106
	v_max_f32_e32 v93, 0, v107
	v_max_f32_e32 v95, 0, v100
	v_pk_mul_f32 v[80:81], v[80:81], v[80:81]
	v_pk_mul_f32 v[82:83], v[82:83], v[82:83]
	v_pk_mul_f32 v[84:85], v[84:85], v[84:85]
	v_pk_mul_f32 v[86:87], v[86:87], v[86:87]
	v_pk_mul_f32 v[88:89], v[88:89], v[88:89]
	v_pk_mul_f32 v[90:91], v[90:91], v[90:91]
	v_pk_mul_f32 v[92:93], v[92:93], v[92:93]
	v_pk_mul_f32 v[94:95], v[94:95], v[94:95]
	v_cvt_pk_bf16_f32 v80, v80, v81
	v_cvt_pk_bf16_f32 v81, v84, v85
	v_cvt_pk_bf16_f32 v82, v82, v83
	v_cvt_pk_bf16_f32 v83, v86, v87
	v_cvt_pk_bf16_f32 v84, v88, v89
	v_cvt_pk_bf16_f32 v85, v92, v93
	v_cvt_pk_bf16_f32 v86, v90, v91
	v_cvt_pk_bf16_f32 v87, v94, v95
	global_store_dwordx4 v[98:99], v[80:83], off
	global_store_dwordx4 v[96:97], v[84:87], off offset:256
	s_nop 0
	v_add_co_u32_e32 v82, vcc, s19, v138
	v_lshl_add_u64 v[80:81], v[138:139], 0, s[26:27]
	s_nop 0
	v_addc_co_u32_e32 v83, vcc, 0, v139, vcc
	s_mov_b32 s19, 0x200000
	s_mov_b64 s[26:27], 0x200000
	v_mov_b32_e32 v84, v202
	v_mul_f32_e32 v76, v76, v84
	v_mul_f32_e32 v72, v72, v84
	v_mul_f32_e32 v77, v77, v84
	v_mul_f32_e32 v73, v73, v84
	v_mul_f32_e32 v78, v78, v84
	v_mul_f32_e32 v74, v74, v84
	v_mul_f32_e32 v79, v79, v84
	v_mul_f32_e32 v75, v75, v84
	v_mul_f32_e32 v85, v68, v84
	v_mul_f32_e32 v86, v64, v84
	v_mul_f32_e32 v87, v69, v84
	v_mul_f32_e32 v88, v65, v84
	v_mul_f32_e32 v89, v70, v84
	v_mul_f32_e32 v90, v66, v84
	v_mul_f32_e32 v91, v71, v84
	v_mul_f32_e32 v84, v67, v84
	v_max_f32_e32 v64, 0, v76
	v_max_f32_e32 v66, 0, v72
	v_max_f32_e32 v65, 0, v77
	v_max_f32_e32 v67, 0, v73
	v_max_f32_e32 v68, 0, v78
	v_max_f32_e32 v70, 0, v74
	v_max_f32_e32 v69, 0, v79
	v_max_f32_e32 v71, 0, v75
	v_max_f32_e32 v72, 0, v85
	v_max_f32_e32 v74, 0, v86
	v_max_f32_e32 v73, 0, v87
	v_max_f32_e32 v75, 0, v88
	v_max_f32_e32 v76, 0, v89
	v_max_f32_e32 v78, 0, v90
	v_max_f32_e32 v77, 0, v91
	v_max_f32_e32 v79, 0, v84
	v_pk_mul_f32 v[64:65], v[64:65], v[64:65]
	v_pk_mul_f32 v[66:67], v[66:67], v[66:67]
	v_pk_mul_f32 v[68:69], v[68:69], v[68:69]
	v_pk_mul_f32 v[70:71], v[70:71], v[70:71]
	v_pk_mul_f32 v[72:73], v[72:73], v[72:73]
	v_pk_mul_f32 v[74:75], v[74:75], v[74:75]
	v_pk_mul_f32 v[76:77], v[76:77], v[76:77]
	v_pk_mul_f32 v[78:79], v[78:79], v[78:79]
	v_cvt_pk_bf16_f32 v64, v64, v65
	v_cvt_pk_bf16_f32 v65, v68, v69
	v_cvt_pk_bf16_f32 v66, v66, v67
	v_cvt_pk_bf16_f32 v67, v70, v71
	v_cvt_pk_bf16_f32 v68, v72, v73
	v_cvt_pk_bf16_f32 v69, v76, v77
	v_cvt_pk_bf16_f32 v70, v74, v75
	v_cvt_pk_bf16_f32 v71, v78, v79
	global_store_dwordx4 v[82:83], v[64:67], off
	global_store_dwordx4 v[80:81], v[68:71], off offset:256
	s_nop 0
	v_add_co_u32_e32 v66, vcc, s19, v138
	v_lshl_add_u64 v[64:65], v[138:139], 0, s[26:27]
	s_nop 0
	v_addc_co_u32_e32 v67, vcc, 0, v139, vcc
	s_mov_b32 s19, 0x240000
	s_mov_b64 s[26:27], 0x240000
	v_mov_b32_e32 v68, v203
	v_mul_f32_e32 v60, v60, v68
	v_mul_f32_e32 v56, v56, v68
	v_mul_f32_e32 v61, v61, v68
	v_mul_f32_e32 v57, v57, v68
	v_mul_f32_e32 v62, v62, v68
	v_mul_f32_e32 v58, v58, v68
	v_mul_f32_e32 v63, v63, v68
	v_mul_f32_e32 v59, v59, v68
	v_mul_f32_e32 v69, v52, v68
	v_mul_f32_e32 v70, v48, v68
	v_mul_f32_e32 v71, v53, v68
	v_mul_f32_e32 v72, v49, v68
	v_mul_f32_e32 v73, v54, v68
	v_mul_f32_e32 v74, v50, v68
	v_mul_f32_e32 v75, v55, v68
	v_mul_f32_e32 v68, v51, v68
	v_max_f32_e32 v48, 0, v60
	v_max_f32_e32 v50, 0, v56
	v_max_f32_e32 v49, 0, v61
	v_max_f32_e32 v51, 0, v57
	v_max_f32_e32 v52, 0, v62
	v_max_f32_e32 v54, 0, v58
	v_max_f32_e32 v53, 0, v63
	v_max_f32_e32 v55, 0, v59
	v_max_f32_e32 v56, 0, v69
	v_max_f32_e32 v58, 0, v70
	v_max_f32_e32 v57, 0, v71
	v_max_f32_e32 v59, 0, v72
	v_max_f32_e32 v60, 0, v73
	v_max_f32_e32 v62, 0, v74
	v_max_f32_e32 v61, 0, v75
	v_max_f32_e32 v63, 0, v68
	v_pk_mul_f32 v[48:49], v[48:49], v[48:49]
	v_pk_mul_f32 v[50:51], v[50:51], v[50:51]
	v_pk_mul_f32 v[52:53], v[52:53], v[52:53]
	v_pk_mul_f32 v[54:55], v[54:55], v[54:55]
	v_pk_mul_f32 v[56:57], v[56:57], v[56:57]
	v_pk_mul_f32 v[58:59], v[58:59], v[58:59]
	v_pk_mul_f32 v[60:61], v[60:61], v[60:61]
	v_pk_mul_f32 v[62:63], v[62:63], v[62:63]
	v_cvt_pk_bf16_f32 v48, v48, v49
	v_cvt_pk_bf16_f32 v49, v52, v53
	v_cvt_pk_bf16_f32 v50, v50, v51
	v_cvt_pk_bf16_f32 v51, v54, v55
	v_cvt_pk_bf16_f32 v52, v56, v57
	v_cvt_pk_bf16_f32 v53, v60, v61
	v_cvt_pk_bf16_f32 v54, v58, v59
	v_cvt_pk_bf16_f32 v55, v62, v63
	global_store_dwordx4 v[66:67], v[48:51], off
	global_store_dwordx4 v[64:65], v[52:55], off offset:256
	s_nop 0
	v_add_co_u32_e32 v50, vcc, s19, v138
	v_lshl_add_u64 v[48:49], v[138:139], 0, s[26:27]
	s_nop 0
	v_addc_co_u32_e32 v51, vcc, 0, v139, vcc
	s_mov_b32 s19, 0x280000
	s_mov_b64 s[26:27], 0x280000
	v_mov_b32_e32 v52, v204
	v_mul_f32_e32 v44, v44, v52
	v_mul_f32_e32 v40, v40, v52
	v_mul_f32_e32 v45, v45, v52
	v_mul_f32_e32 v41, v41, v52
	v_mul_f32_e32 v46, v46, v52
	v_mul_f32_e32 v42, v42, v52
	v_mul_f32_e32 v47, v47, v52
	v_mul_f32_e32 v43, v43, v52
	v_mul_f32_e32 v53, v36, v52
; #define PG8_BAR __builtin_amdgcn_s_barrier()
; DI u32x4 pk8(f32x4 a, f32x4 b) { u32x4 w; w.x = pk2(a[0], a[1]); w.y = pk2(a[2], a[3]); w.z = pk2(b[0], b[1]); w.w = pk2(b[2], b[3]); return w; }
; template <class Epi, class Sched, bool ALIGN_EPI = false, bool SP2 = false>
; __device__ __forceinline__ void gemm_phase(PG8_LAS unsigned char* lds, const Gemm g, const Sched& S, const Epi& E) {
;     ...
;         if constexpr (ALIGN_EPI) { if (wr == 1) PG8_BAR; }
;     DI void operator()(const f32x4 (&acc)[2][2][4][2], const Unit& u, int wr, int wc, int fr, int fq) const {
;     ...
;         const int row0 = u.pm * BM + wr * 64 + fr, col0 = u.pn * BM + wc * 32 + 8 * fq;
; #pragma unroll
;         for (int ai = 0; ai < 2; ++ai)
; #pragma unroll
;             for (int m = 0; m < 4; ++m) { bf16* rowp = O + (size_t)(row0 + ai * HALF + m * 16) * ldc + col0; const float rs = RS[row0 + ai * HALF + m * 16];
; #pragma unroll
;                 for (int bj = 0; bj < 2; ++bj) { f32x4 v0 = acc[ai][bj][m][0], v1 = acc[ai][bj][m][1];
; #pragma unroll
;                     for (int e = 0; e < 4; ++e) { const float a = fmaxf(v0[e] * rs, 0.f), b = fmaxf(v1[e] * rs, 0.f); v0[e] = a * a; v1[e] = b * b; }
;                     *(u32x4*)(rowp + bj * HALF) = pk8(v0, v1); } }
	v_mul_f32_e32 v54, v32, v52
	v_mul_f32_e32 v55, v37, v52
	v_mul_f32_e32 v56, v33, v52
	v_mul_f32_e32 v57, v38, v52
	v_mul_f32_e32 v58, v34, v52
	v_mul_f32_e32 v59, v39, v52
	v_mul_f32_e32 v52, v35, v52
	v_max_f32_e32 v32, 0, v44
	v_max_f32_e32 v34, 0, v40
	v_max_f32_e32 v33, 0, v45
	v_max_f32_e32 v35, 0, v41
	v_max_f32_e32 v36, 0, v46
	v_max_f32_e32 v38, 0, v42
	v_max_f32_e32 v37, 0, v47
	v_max_f32_e32 v39, 0, v43
	v_max_f32_e32 v40, 0, v53
	v_max_f32_e32 v42, 0, v54
	v_max_f32_e32 v41, 0, v55
	v_max_f32_e32 v43, 0, v56
	v_max_f32_e32 v44, 0, v57
	v_max_f32_e32 v46, 0, v58
	v_max_f32_e32 v45, 0, v59
	v_max_f32_e32 v47, 0, v52
	v_pk_mul_f32 v[32:33], v[32:33], v[32:33]
	v_pk_mul_f32 v[34:35], v[34:35], v[34:35]
	v_pk_mul_f32 v[36:37], v[36:37], v[36:37]
	v_pk_mul_f32 v[38:39], v[38:39], v[38:39]
	v_pk_mul_f32 v[40:41], v[40:41], v[40:41]
	v_pk_mul_f32 v[42:43], v[42:43], v[42:43]
	v_pk_mul_f32 v[44:45], v[44:45], v[44:45]
	v_pk_mul_f32 v[46:47], v[46:47], v[46:47]
	v_cvt_pk_bf16_f32 v32, v32, v33
	v_cvt_pk_bf16_f32 v33, v36, v37
	v_cvt_pk_bf16_f32 v34, v34, v35
	v_cvt_pk_bf16_f32 v35, v38, v39
	v_cvt_pk_bf16_f32 v36, v40, v41
	v_cvt_pk_bf16_f32 v37, v44, v45
	v_cvt_pk_bf16_f32 v38, v42, v43
	v_cvt_pk_bf16_f32 v39, v46, v47
	global_store_dwordx4 v[50:51], v[32:35], off
	global_store_dwordx4 v[48:49], v[36:39], off offset:256
	s_nop 0
	v_add_co_u32_e32 v34, vcc, s19, v138
	v_lshl_add_u64 v[32:33], v[138:139], 0, s[26:27]
	s_nop 0
	v_addc_co_u32_e32 v35, vcc, 0, v139, vcc
	s_andn2_b64 vcc, exec, s[0:1]
	s_mov_b64 s[0:1], 0x2c0000
	v_mov_b32_e32 v36, v205
	v_mul_f32_e32 v28, v28, v36
	v_mul_f32_e32 v24, v24, v36
	v_mul_f32_e32 v29, v29, v36
	v_mul_f32_e32 v25, v25, v36
	v_mul_f32_e32 v30, v30, v36
	v_mul_f32_e32 v26, v26, v36
	v_mul_f32_e32 v31, v31, v36
	v_mul_f32_e32 v27, v27, v36
	v_mul_f32_e32 v37, v20, v36
	v_mul_f32_e32 v38, v16, v36
	v_mul_f32_e32 v39, v21, v36
	v_mul_f32_e32 v40, v17, v36
	v_mul_f32_e32 v41, v22, v36
	v_mul_f32_e32 v42, v18, v36
	v_mul_f32_e32 v43, v23, v36
	v_mul_f32_e32 v36, v19, v36
	v_max_f32_e32 v16, 0, v28
	v_max_f32_e32 v18, 0, v24
	v_max_f32_e32 v17, 0, v29
	v_max_f32_e32 v19, 0, v25
	v_max_f32_e32 v20, 0, v30
	v_max_f32_e32 v22, 0, v26
	v_max_f32_e32 v21, 0, v31
	v_max_f32_e32 v23, 0, v27
	v_max_f32_e32 v24, 0, v37
	v_max_f32_e32 v26, 0, v38
	v_max_f32_e32 v25, 0, v39
	v_max_f32_e32 v27, 0, v40
	v_max_f32_e32 v28, 0, v41
	v_max_f32_e32 v30, 0, v42
	v_max_f32_e32 v29, 0, v43
	v_max_f32_e32 v31, 0, v36
	v_pk_mul_f32 v[16:17], v[16:17], v[16:17]
	v_pk_mul_f32 v[18:19], v[18:19], v[18:19]
	v_pk_mul_f32 v[20:21], v[20:21], v[20:21]
	v_pk_mul_f32 v[22:23], v[22:23], v[22:23]
	v_pk_mul_f32 v[24:25], v[24:25], v[24:25]
	v_pk_mul_f32 v[26:27], v[26:27], v[26:27]
	v_pk_mul_f32 v[28:29], v[28:29], v[28:29]
	v_pk_mul_f32 v[30:31], v[30:31], v[30:31]
	v_cvt_pk_bf16_f32 v16, v16, v17
	v_cvt_pk_bf16_f32 v17, v20, v21
	v_cvt_pk_bf16_f32 v18, v18, v19
	v_cvt_pk_bf16_f32 v19, v22, v23
	v_cvt_pk_bf16_f32 v20, v24, v25
	v_cvt_pk_bf16_f32 v21, v28, v29
	v_cvt_pk_bf16_f32 v22, v26, v27
	v_cvt_pk_bf16_f32 v23, v30, v31
	global_store_dwordx4 v[34:35], v[16:19], off
	global_store_dwordx4 v[32:33], v[20:23], off offset:256
	s_nop 0
	v_lshl_add_u64 v[16:17], v[138:139], 0, s[0:1]
	s_mov_b32 s0, 0x2c0000
	v_add_co_u32_e64 v18, s[0:1], s0, v138
	v_mov_b32_e32 v20, v206
	v_mul_f32_e32 v12, v12, v20
	v_mul_f32_e32 v8, v8, v20
	v_mul_f32_e32 v13, v13, v20
	v_mul_f32_e32 v9, v9, v20
	v_mul_f32_e32 v14, v14, v20
	v_mul_f32_e32 v10, v10, v20
	v_mul_f32_e32 v15, v15, v20
	v_mul_f32_e32 v11, v11, v20
	v_mul_f32_e32 v21, v4, v20
	v_mul_f32_e32 v22, v0, v20
	v_mul_f32_e32 v23, v5, v20
	v_mul_f32_e32 v24, v1, v20
	v_mul_f32_e32 v25, v6, v20
	v_mul_f32_e32 v26, v2, v20
	v_mul_f32_e32 v27, v7, v20
	v_mul_f32_e32 v20, v3, v20
	v_max_f32_e32 v0, 0, v12
	v_max_f32_e32 v2, 0, v8
	v_max_f32_e32 v1, 0, v13
	v_max_f32_e32 v3, 0, v9
	v_max_f32_e32 v4, 0, v14
	v_max_f32_e32 v6, 0, v10
	v_max_f32_e32 v5, 0, v15
	v_max_f32_e32 v7, 0, v11
	v_addc_co_u32_e64 v19, s[0:1], 0, v139, s[0:1]
	v_max_f32_e32 v8, 0, v21
	v_max_f32_e32 v10, 0, v22
	v_max_f32_e32 v9, 0, v23
	v_max_f32_e32 v11, 0, v24
	v_max_f32_e32 v12, 0, v25
	v_max_f32_e32 v14, 0, v26
	v_max_f32_e32 v13, 0, v27
	v_max_f32_e32 v15, 0, v20
	v_pk_mul_f32 v[0:1], v[0:1], v[0:1]
	v_pk_mul_f32 v[2:3], v[2:3], v[2:3]
	v_pk_mul_f32 v[4:5], v[4:5], v[4:5]
	v_pk_mul_f32 v[6:7], v[6:7], v[6:7]
	v_pk_mul_f32 v[8:9], v[8:9], v[8:9]
	v_pk_mul_f32 v[10:11], v[10:11], v[10:11]
	v_pk_mul_f32 v[12:13], v[12:13], v[12:13]
	v_pk_mul_f32 v[14:15], v[14:15], v[14:15]
	v_cvt_pk_bf16_f32 v0, v0, v1
	v_cvt_pk_bf16_f32 v1, v4, v5
	v_cvt_pk_bf16_f32 v2, v2, v3
	v_cvt_pk_bf16_f32 v3, v6, v7
	s_mov_b64 s[0:1], -1
	v_cvt_pk_bf16_f32 v4, v8, v9
	v_cvt_pk_bf16_f32 v5, v12, v13
	v_cvt_pk_bf16_f32 v6, v10, v11
	v_cvt_pk_bf16_f32 v7, v14, v15
	global_store_dwordx4 v[18:19], v[0:3], off
	global_store_dwordx4 v[16:17], v[4:7], off offset:256
	s_nop 0
	s_nop 0
	s_nop 0
	s_cbranch_vccnz .LBB0_1050
	s_andn2_b64 vcc, exec, s[2:3]
	s_cbranch_vccnz .LBB0_1049
	s_barrier
	s_branch .LBB0_1049

; #define LAS __attribute__((address_space(3)))
; #define MFMA16(a, b, c) __builtin_amdgcn_mfma_f32_16x16x32_bf16((a), (b), (c), 0, 0, 0)
; DI unsigned short f2bf1(float a) { return (unsigned short)(pk2(a, 0.f) & 0xffffu); }
;     ...
;     const int ntask = (N / (16 * NC)) * KSPLIT, kr = K / KSPLIT, kw = kr / 8;
;     LAS float* red = (LAS float*)lds;
;     for (int t = G - 1 - cu; t < ntask; t += G) {
;         const int cgi = t / KSPLIT, kh = t - cgi * KSPLIT, n0 = cgi * 16 * NC, kbeg = kh * kr + wid * kw + 8 * fq;
;         const bf16* wp = WT + (size_t)(n0 + fr) * K + kbeg;
;         const bf16* ap0 = As + (size_t)fr * K + kbeg; const bf16* ap1 = ap0 + (size_t)16 * K;
;         f32x4 acc[NC][2];
; #pragma unroll
;         for (int c = 0; c < NC; ++c) { acc[c][0] = (f32x4){0.f, 0.f, 0.f, 0.f}; acc[c][1] = (f32x4){0.f, 0.f, 0.f, 0.f}; }
; #pragma unroll 4
;         for (int k = 0; k < kw; k += 32) {
;             const bf16x8 a0 = *(const bf16x8*)(ap0 + k), a1 = *(const bf16x8*)(ap1 + k);
; #pragma unroll
;             for (int c = 0; c < NC; ++c) { const bf16x8 w = *(const bf16x8*)(wp + (size_t)c * 16 * K + k); acc[c][0] = MFMA16(w, a0, acc[c][0]); acc[c][1] = MFMA16(w, a1, acc[c][1]); }
;         }
; #pragma unroll
;         for (int c = 0; c < NC; ++c) { *(LAS f32x4*)(red + (wid * NC + c) * 512 + fr * 16 + 4 * fq) = acc[c][0]; *(LAS f32x4*)(red + (wid * NC + c) * 512 + (16 + fr) * 16 + 4 * fq) = acc[c][1]; }
;         __syncthreads();
; #pragma unroll
;         for (int c = 0; c < NC; ++c) {
;             float s = 0.f;
; #pragma unroll
;             for (int w = 0; w < 8; ++w) s += red[(w * NC + c) * 512 + tid];
;             const int row = tid >> 4, n = tid & 15, nn = n0 + 16 * c;
;             if (rsv) s *= rsv[row];
;             if (MODE == 0) { const int col = evenperm ? even_src32(nn >> 5) + (nn & 16) + n : nn + n; outf[(size_t)(kh * 32 + row) * ldo + col] = s; }
;             else if (MODE == 1) { const float r = fmaxf(s, 0.f); outb[(size_t)row * ldo + nn + n] = f2bf1(r * r); }
;             else outb[(size_t)row * ldo + nn + n] = f2bf1(s);
;         }
.LBB0_1086:
	v_lshl_add_u64 v[36:37], v[28:29], 0, v[20:21]
	s_mov_b32 s4, 0x18400000
	v_add_co_u32_e32 v44, vcc, s4, v36
	s_mov_b32 s4, 0x18410000
	s_nop 0
	v_addc_co_u32_e32 v45, vcc, 0, v37, vcc
	v_add_co_u32_e32 v46, vcc, s4, v36
	v_lshl_add_u64 v[48:49], v[26:27], 0, v[20:21]
	s_nop 0
	v_addc_co_u32_e32 v47, vcc, 0, v37, vcc
	s_mov_b32 s4, 0x6400000
	v_add_co_u32_e32 v50, vcc, s4, v48
	s_nop 1
	v_addc_co_u32_e32 v51, vcc, 0, v49, vcc
	s_mov_b32 s4, 0x6410000
	v_add_co_u32_e32 v48, vcc, s4, v48
	s_nop 1
	v_addc_co_u32_e32 v49, vcc, 0, v49, vcc
	global_load_dwordx4 v[52:55], v[44:45], off
	global_load_dwordx4 v[56:59], v[46:47], off
	global_load_dwordx4 v[60:63], v[50:51], off
	global_load_dwordx4 v[64:67], v[48:49], off
	global_load_dwordx4 v[68:71], v[44:45], off offset:64
	global_load_dwordx4 v[72:75], v[46:47], off offset:64
	global_load_dwordx4 v[76:79], v[50:51], off offset:64
	global_load_dwordx4 v[80:83], v[48:49], off offset:64
	global_load_dwordx4 v[84:87], v[44:45], off offset:128
	global_load_dwordx4 v[88:91], v[46:47], off offset:128
	global_load_dwordx4 v[92:95], v[50:51], off offset:128
	global_load_dwordx4 v[96:99], v[48:49], off offset:128
	global_load_dwordx4 v[100:103], v[44:45], off offset:192
	global_load_dwordx4 v[104:107], v[46:47], off offset:192
	global_load_dwordx4 v[108:111], v[50:51], off offset:192
	global_load_dwordx4 v[112:115], v[48:49], off offset:192
	global_load_dwordx4 v[116:119], v[44:45], off offset:256
	global_load_dwordx4 v[120:123], v[46:47], off offset:256
	global_load_dwordx4 v[124:127], v[50:51], off offset:256
	global_load_dwordx4 v[164:167], v[48:49], off offset:256
	global_load_dwordx4 v[168:171], v[44:45], off offset:320
	global_load_dwordx4 v[172:175], v[46:47], off offset:320
	global_load_dwordx4 v[176:179], v[50:51], off offset:320
	global_load_dwordx4 v[180:183], v[48:49], off offset:320
	global_load_dwordx4 v[184:187], v[44:45], off offset:384
	global_load_dwordx4 v[188:191], v[46:47], off offset:384
	global_load_dwordx4 v[192:195], v[50:51], off offset:384
	global_load_dwordx4 v[196:199], v[48:49], off offset:384
	global_load_dwordx4 v[200:203], v[44:45], off offset:448
	global_load_dwordx4 v[204:207], v[46:47], off offset:448
	global_load_dwordx4 v[208:211], v[50:51], off offset:448
	global_load_dwordx4 v[212:215], v[48:49], off offset:448
	s_waitcnt vmcnt(28)
	v_mfma_f32_16x16x32_bf16 v[8:11], v[60:63], v[52:55], v[8:11]
	v_mfma_f32_16x16x32_bf16 v[12:15], v[60:63], v[56:59], v[12:15]
	v_mfma_f32_16x16x32_bf16 v[4:7], v[64:67], v[52:55], v[4:7]
	v_mfma_f32_16x16x32_bf16 v[0:3], v[64:67], v[56:59], v[0:3]
	s_waitcnt vmcnt(24)
	v_mfma_f32_16x16x32_bf16 v[8:11], v[76:79], v[68:71], v[8:11]
	v_mfma_f32_16x16x32_bf16 v[12:15], v[76:79], v[72:75], v[12:15]
	v_mfma_f32_16x16x32_bf16 v[4:7], v[80:83], v[68:71], v[4:7]
	v_mfma_f32_16x16x32_bf16 v[0:3], v[80:83], v[72:75], v[0:3]
	s_waitcnt vmcnt(20)
	v_mfma_f32_16x16x32_bf16 v[8:11], v[92:95], v[84:87], v[8:11]
	v_mfma_f32_16x16x32_bf16 v[12:15], v[92:95], v[88:91], v[12:15]
	v_mfma_f32_16x16x32_bf16 v[4:7], v[96:99], v[84:87], v[4:7]
	v_mfma_f32_16x16x32_bf16 v[0:3], v[96:99], v[88:91], v[0:3]
	s_waitcnt vmcnt(16)
	v_mfma_f32_16x16x32_bf16 v[8:11], v[108:111], v[100:103], v[8:11]
	v_mfma_f32_16x16x32_bf16 v[12:15], v[108:111], v[104:107], v[12:15]
	v_mfma_f32_16x16x32_bf16 v[4:7], v[112:115], v[100:103], v[4:7]
	v_mfma_f32_16x16x32_bf16 v[0:3], v[112:115], v[104:107], v[0:3]
	s_waitcnt vmcnt(12)
	v_mfma_f32_16x16x32_bf16 v[8:11], v[124:127], v[116:119], v[8:11]
	v_mfma_f32_16x16x32_bf16 v[12:15], v[124:127], v[120:123], v[12:15]
	v_mfma_f32_16x16x32_bf16 v[4:7], v[164:167], v[116:119], v[4:7]
	v_mfma_f32_16x16x32_bf16 v[0:3], v[164:167], v[120:123], v[0:3]
	s_waitcnt vmcnt(8)
	v_mfma_f32_16x16x32_bf16 v[8:11], v[176:179], v[168:171], v[8:11]
	v_mfma_f32_16x16x32_bf16 v[12:15], v[176:179], v[172:175], v[12:15]
	v_mfma_f32_16x16x32_bf16 v[4:7], v[180:183], v[168:171], v[4:7]
	v_mfma_f32_16x16x32_bf16 v[0:3], v[180:183], v[172:175], v[0:3]
	s_waitcnt vmcnt(4)
	v_mfma_f32_16x16x32_bf16 v[8:11], v[192:195], v[184:187], v[8:11]
	v_mfma_f32_16x16x32_bf16 v[12:15], v[192:195], v[188:191], v[12:15]
	v_mfma_f32_16x16x32_bf16 v[4:7], v[196:199], v[184:187], v[4:7]
	v_mfma_f32_16x16x32_bf16 v[0:3], v[196:199], v[188:191], v[0:3]
	s_waitcnt vmcnt(0)
	v_mfma_f32_16x16x32_bf16 v[8:11], v[208:211], v[200:203], v[8:11]
	v_mfma_f32_16x16x32_bf16 v[12:15], v[208:211], v[204:207], v[12:15]
	v_mfma_f32_16x16x32_bf16 v[4:7], v[212:215], v[200:203], v[4:7]
	v_mfma_f32_16x16x32_bf16 v[0:3], v[212:215], v[204:207], v[0:3]
	s_nop 1
	ds_write_b128 v31, v[8:11]
	ds_write_b128 v31, v[12:15] offset:1024
	s_nop 1
	ds_write_b128 v31, v[4:7] offset:2048
	ds_write_b128 v31, v[0:3] offset:3072
	s_waitcnt lgkmcnt(0)
	s_barrier
	ds_read2st64_b32 v[0:1], v30 offset1:8
	ds_read2st64_b32 v[2:3], v30 offset0:16 offset1:24
	ds_read2st64_b32 v[4:5], v30 offset0:32 offset1:40
	ds_read2st64_b32 v[6:7], v30 offset0:48 offset1:56
	ds_read2st64_b32 v[8:9], v30 offset0:64 offset1:72
	s_waitcnt lgkmcnt(4)
	v_add_f32_e32 v0, 0, v0
	s_waitcnt lgkmcnt(3)
	v_add_f32_e32 v0, v0, v2
	global_load_dword v2, v[18:19], off
	ds_read2st64_b32 v[10:11], v30 offset0:80 offset1:88
	ds_read2st64_b32 v[12:13], v30 offset0:96 offset1:104
	s_waitcnt lgkmcnt(4)
	v_add_f32_e32 v0, v0, v4
	ds_read2st64_b32 v[14:15], v30 offset0:112 offset1:120
	s_waitcnt lgkmcnt(4)
	v_add_f32_e32 v0, v0, v6
	s_waitcnt lgkmcnt(3)
	v_add_f32_e32 v0, v0, v8
	s_waitcnt lgkmcnt(2)
	v_add_f32_e32 v0, v0, v10
	s_waitcnt lgkmcnt(1)
	v_add_f32_e32 v0, v0, v12
	s_waitcnt lgkmcnt(0)
	v_add_f32_e32 v0, v0, v14
	s_lshl_b32 s4, s2, 5
	s_ashr_i32 s5, s4, 31
	v_lshl_add_u64 v[26:27], s[4:5], 1, v[16:17]
	s_add_i32 s2, s2, s90
	v_add_u32_e32 v24, s65, v24
	s_cmpk_gt_i32 s2, 0xff
	s_waitcnt vmcnt(0)
	v_mul_f32_e32 v0, v0, v2
	v_max_f32_e32 v0, 0, v0
	v_mul_f32_e32 v0, v0, v0
	v_cvt_pk_bf16_f32 v0, v0, s0
	global_store_short v[26:27], v0, off
	v_add_f32_e32 v0, 0, v1
	v_add_f32_e32 v0, v0, v3
	v_add_f32_e32 v0, v0, v5
	v_add_f32_e32 v0, v0, v7
	v_add_f32_e32 v0, v0, v9
	v_add_f32_e32 v0, v0, v11
	v_add_f32_e32 v0, v0, v13
	v_add_f32_e32 v0, v0, v15
	v_mul_f32_e32 v0, v2, v0
	v_max_f32_e32 v0, 0, v0
	v_mul_f32_e32 v0, v0, v0
	v_cvt_pk_bf16_f32 v0, v0, s0
	global_store_short v[26:27], v0, off offset:32
	s_barrier
	s_cbranch_scc0 .LBB0_1085

; #define LAS __attribute__((address_space(3)))
; #define MFMA16(a, b, c) __builtin_amdgcn_mfma_f32_16x16x32_bf16((a), (b), (c), 0, 0, 0)
; DI unsigned short f2bf1(float a) { return (unsigned short)(pk2(a, 0.f) & 0xffffu); }
;     ...
;     const int ntask = (N / (16 * NC)) * KSPLIT, kr = K / KSPLIT, kw = kr / 8;
;     LAS float* red = (LAS float*)lds;
;     for (int t = G - 1 - cu; t < ntask; t += G) {
;         const int cgi = t / KSPLIT, kh = t - cgi * KSPLIT, n0 = cgi * 16 * NC, kbeg = kh * kr + wid * kw + 8 * fq;
;         const bf16* wp = WT + (size_t)(n0 + fr) * K + kbeg;
;         const bf16* ap0 = As + (size_t)fr * K + kbeg; const bf16* ap1 = ap0 + (size_t)16 * K;
;         f32x4 acc[NC][2];
; #pragma unroll
;         for (int c = 0; c < NC; ++c) { acc[c][0] = (f32x4){0.f, 0.f, 0.f, 0.f}; acc[c][1] = (f32x4){0.f, 0.f, 0.f, 0.f}; }
; #pragma unroll 4
;         for (int k = 0; k < kw; k += 32) {
;             const bf16x8 a0 = *(const bf16x8*)(ap0 + k), a1 = *(const bf16x8*)(ap1 + k);
; #pragma unroll
;             for (int c = 0; c < NC; ++c) { const bf16x8 w = *(const bf16x8*)(wp + (size_t)c * 16 * K + k); acc[c][0] = MFMA16(w, a0, acc[c][0]); acc[c][1] = MFMA16(w, a1, acc[c][1]); }
;         }
; #pragma unroll
;         for (int c = 0; c < NC; ++c) { *(LAS f32x4*)(red + (wid * NC + c) * 512 + fr * 16 + 4 * fq) = acc[c][0]; *(LAS f32x4*)(red + (wid * NC + c) * 512 + (16 + fr) * 16 + 4 * fq) = acc[c][1]; }
;         __syncthreads();
; #pragma unroll
;         for (int c = 0; c < NC; ++c) {
;             float s = 0.f;
; #pragma unroll
;             for (int w = 0; w < 8; ++w) s += red[(w * NC + c) * 512 + tid];
;             const int row = tid >> 4, n = tid & 15, nn = n0 + 16 * c;
;             if (rsv) s *= rsv[row];
;             if (MODE == 0) { const int col = evenperm ? even_src32(nn >> 5) + (nn & 16) + n : nn + n; outf[(size_t)(kh * 32 + row) * ldo + col] = s; }
;             else if (MODE == 1) { const float r = fmaxf(s, 0.f); outb[(size_t)row * ldo + nn + n] = f2bf1(r * r); }
;             else outb[(size_t)row * ldo + nn + n] = f2bf1(s);
;         }
.LBB0_1298:
	v_lshl_add_u64 v[36:37], v[24:25], 0, v[20:21]
	s_mov_b32 s7, 0x2e100000
	v_add_co_u32_e32 v44, vcc, s7, v36
	s_mov_b32 s7, 0x2e140000
	s_nop 0
	v_addc_co_u32_e32 v45, vcc, 0, v37, vcc
	v_add_co_u32_e32 v46, vcc, s7, v36
	v_lshl_add_u64 v[48:49], v[22:23], 0, v[20:21]
	s_nop 0
	v_addc_co_u32_e32 v47, vcc, 0, v37, vcc
	s_mov_b32 s7, 0xe400000
	v_add_co_u32_e32 v50, vcc, s7, v48
	s_nop 1
	v_addc_co_u32_e32 v51, vcc, 0, v49, vcc
	s_mov_b32 s7, 0xe440000
	v_add_co_u32_e32 v48, vcc, s7, v48
	s_nop 1
	v_addc_co_u32_e32 v49, vcc, 0, v49, vcc
	global_load_dwordx4 v[52:55], v[44:45], off
	global_load_dwordx4 v[56:59], v[46:47], off
	global_load_dwordx4 v[60:63], v[50:51], off
	global_load_dwordx4 v[64:67], v[48:49], off
	global_load_dwordx4 v[68:71], v[44:45], off offset:64
	global_load_dwordx4 v[72:75], v[46:47], off offset:64
	global_load_dwordx4 v[76:79], v[50:51], off offset:64
	global_load_dwordx4 v[80:83], v[48:49], off offset:64
	global_load_dwordx4 v[84:87], v[44:45], off offset:128
	global_load_dwordx4 v[88:91], v[46:47], off offset:128
	global_load_dwordx4 v[92:95], v[50:51], off offset:128
	global_load_dwordx4 v[96:99], v[48:49], off offset:128
	global_load_dwordx4 v[100:103], v[44:45], off offset:192
	global_load_dwordx4 v[104:107], v[46:47], off offset:192
	global_load_dwordx4 v[108:111], v[50:51], off offset:192
	global_load_dwordx4 v[112:115], v[48:49], off offset:192
	global_load_dwordx4 v[116:119], v[44:45], off offset:256
	global_load_dwordx4 v[120:123], v[46:47], off offset:256
	global_load_dwordx4 v[124:127], v[50:51], off offset:256
	global_load_dwordx4 v[164:167], v[48:49], off offset:256
	global_load_dwordx4 v[168:171], v[44:45], off offset:320
	global_load_dwordx4 v[172:175], v[46:47], off offset:320
	global_load_dwordx4 v[176:179], v[50:51], off offset:320
	global_load_dwordx4 v[180:183], v[48:49], off offset:320
	global_load_dwordx4 v[184:187], v[44:45], off offset:384
	global_load_dwordx4 v[188:191], v[46:47], off offset:384
	global_load_dwordx4 v[192:195], v[50:51], off offset:384
	global_load_dwordx4 v[196:199], v[48:49], off offset:384
	global_load_dwordx4 v[200:203], v[44:45], off offset:448
	global_load_dwordx4 v[204:207], v[46:47], off offset:448
	global_load_dwordx4 v[208:211], v[50:51], off offset:448
	global_load_dwordx4 v[212:215], v[48:49], off offset:448
	s_waitcnt vmcnt(28)
	v_mfma_f32_16x16x32_bf16 v[8:11], v[60:63], v[52:55], v[8:11]
	v_mfma_f32_16x16x32_bf16 v[12:15], v[60:63], v[56:59], v[12:15]
	v_mfma_f32_16x16x32_bf16 v[4:7], v[64:67], v[52:55], v[4:7]
	v_mfma_f32_16x16x32_bf16 v[0:3], v[64:67], v[56:59], v[0:3]
	s_waitcnt vmcnt(24)
	v_mfma_f32_16x16x32_bf16 v[8:11], v[76:79], v[68:71], v[8:11]
	v_mfma_f32_16x16x32_bf16 v[12:15], v[76:79], v[72:75], v[12:15]
	v_mfma_f32_16x16x32_bf16 v[4:7], v[80:83], v[68:71], v[4:7]
	v_mfma_f32_16x16x32_bf16 v[0:3], v[80:83], v[72:75], v[0:3]
	s_waitcnt vmcnt(20)
	v_mfma_f32_16x16x32_bf16 v[8:11], v[92:95], v[84:87], v[8:11]
	v_mfma_f32_16x16x32_bf16 v[12:15], v[92:95], v[88:91], v[12:15]
	v_mfma_f32_16x16x32_bf16 v[4:7], v[96:99], v[84:87], v[4:7]
	v_mfma_f32_16x16x32_bf16 v[0:3], v[96:99], v[88:91], v[0:3]
	s_waitcnt vmcnt(16)
	v_mfma_f32_16x16x32_bf16 v[8:11], v[108:111], v[100:103], v[8:11]
	v_mfma_f32_16x16x32_bf16 v[12:15], v[108:111], v[104:107], v[12:15]
	v_mfma_f32_16x16x32_bf16 v[4:7], v[112:115], v[100:103], v[4:7]
	v_mfma_f32_16x16x32_bf16 v[0:3], v[112:115], v[104:107], v[0:3]
	s_waitcnt vmcnt(12)
	v_mfma_f32_16x16x32_bf16 v[8:11], v[124:127], v[116:119], v[8:11]
	v_mfma_f32_16x16x32_bf16 v[12:15], v[124:127], v[120:123], v[12:15]
	v_mfma_f32_16x16x32_bf16 v[4:7], v[164:167], v[116:119], v[4:7]
	v_mfma_f32_16x16x32_bf16 v[0:3], v[164:167], v[120:123], v[0:3]
	s_waitcnt vmcnt(8)
	v_mfma_f32_16x16x32_bf16 v[8:11], v[176:179], v[168:171], v[8:11]
	v_mfma_f32_16x16x32_bf16 v[12:15], v[176:179], v[172:175], v[12:15]
	v_mfma_f32_16x16x32_bf16 v[4:7], v[180:183], v[168:171], v[4:7]
	v_mfma_f32_16x16x32_bf16 v[0:3], v[180:183], v[172:175], v[0:3]
	s_waitcnt vmcnt(4)
	v_mfma_f32_16x16x32_bf16 v[8:11], v[192:195], v[184:187], v[8:11]
	v_mfma_f32_16x16x32_bf16 v[12:15], v[192:195], v[188:191], v[12:15]
	v_mfma_f32_16x16x32_bf16 v[4:7], v[196:199], v[184:187], v[4:7]
	v_mfma_f32_16x16x32_bf16 v[0:3], v[196:199], v[188:191], v[0:3]
	s_waitcnt vmcnt(0)
	v_mfma_f32_16x16x32_bf16 v[8:11], v[208:211], v[200:203], v[8:11]
	v_mfma_f32_16x16x32_bf16 v[12:15], v[208:211], v[204:207], v[12:15]
	v_mfma_f32_16x16x32_bf16 v[4:7], v[212:215], v[200:203], v[4:7]
	v_mfma_f32_16x16x32_bf16 v[0:3], v[212:215], v[204:207], v[0:3]
	s_barrier
	s_nop 1
	ds_write_b128 v29, v[8:11]
	ds_write_b128 v29, v[12:15] offset:1024
	s_nop 1
	ds_write_b128 v29, v[4:7] offset:2048
	ds_write_b128 v29, v[0:3] offset:3072
	s_waitcnt lgkmcnt(0)
	s_barrier
	ds_read2st64_b32 v[2:3], v27 offset1:8
	ds_read2st64_b32 v[4:5], v27 offset0:16 offset1:24
	ds_read2st64_b32 v[6:7], v27 offset0:32 offset1:40
	ds_read2st64_b32 v[8:9], v27 offset0:48 offset1:56
	ds_read2st64_b32 v[10:11], v27 offset0:64 offset1:72
	s_waitcnt lgkmcnt(4)
	v_add_f32_e32 v2, 0, v2
	ds_read2st64_b32 v[12:13], v27 offset0:80 offset1:88
	s_lshl_b32 s5, s5, 2
	s_waitcnt lgkmcnt(4)
	v_add_f32_e32 v2, v2, v4
	ds_read2st64_b32 v[14:15], v27 offset0:96 offset1:104
	s_sub_i32 s5, s4, s5
	s_waitcnt lgkmcnt(4)
	v_add_f32_e32 v2, v2, v6
	ds_read2st64_b32 v[20:21], v27 offset0:112 offset1:120
	v_lshl_add_u32 v0, s5, 5, v28
	s_waitcnt lgkmcnt(4)
	v_add_f32_e32 v2, v2, v8
	v_ashrrev_i32_e32 v1, 31, v0
	s_waitcnt lgkmcnt(3)
	v_add_f32_e32 v2, v2, v10
	v_lshlrev_b64 v[0:1], 13, v[0:1]
	s_waitcnt lgkmcnt(2)
	v_add_f32_e32 v2, v2, v12
	v_lshl_add_u64 v[0:1], s[0:1], 0, v[0:1]
	s_waitcnt lgkmcnt(1)
	v_add_f32_e32 v2, v2, v14
	s_waitcnt lgkmcnt(0)
	v_add_f32_e32 v2, v2, v20
	v_lshl_add_u64 v[0:1], v[18:19], 2, v[0:1]
	global_store_dword v[0:1], v2, off
	v_add_f32_e32 v2, 0, v3
	v_add_f32_e32 v2, v2, v5
	v_add_f32_e32 v2, v2, v7
	v_add_f32_e32 v2, v2, v9
	v_add_f32_e32 v2, v2, v11
	v_add_f32_e32 v2, v2, v13
	v_add_f32_e32 v2, v2, v15
	s_add_i32 s4, s4, s90
	v_add_f32_e32 v2, v2, v21
	v_add_u32_e32 v30, s64, v30
	s_cmpk_gt_i32 s4, 0xff
	global_store_dword v[0:1], v2, off offset:64
	s_barrier
	s_cbranch_scc0 .LBB0_1297
